# scan step with row-pair packed state (52 VALU per step, no lo+hi adds)
# speedup vs baseline: 1.0043x; 1.0043x over previous
.LBB0_390:
	s_and_b32 s3, s2, 1
	s_mul_i32 s8, s3, 0x5000
	v_add_u32_e32 v2, s8, v136
	s_mul_i32 s8, s2, 0xab
	s_bfe_u32 s8, s8, 0x70009
	s_mul_i32 s8, s8, 3
	s_sub_i32 s8, s2, s8
	s_and_b32 s8, s8, 0xff
	s_mulk_i32 s8, 0x1100
	v_add_u32_e32 v3, s8, v137
	v_lshl_add_u32 v1, s3, 12, v137
	ds_read_b128 v[176:179], v2 offset:4096
	ds_read_b128 v[180:183], v2 offset:4112
	ds_read_b128 v[200:203], v2 offset:12288
	ds_read_b128 v[204:207], v2 offset:12304
	ds_read_b64 v[216:217], v3 offset:40960
	ds_read_b128 v[184:187], v2 offset:0
	ds_read_b128 v[188:191], v2 offset:16
	ds_read_b128 v[192:195], v2 offset:8192
	ds_read_b128 v[196:199], v2 offset:8208
	s_waitcnt lgkmcnt(0)
	v_pk_mul_f32 v[164:165], v[72:73], v[176:177] op_sel_hi:[1,0]
	v_pk_mul_f32 v[218:219], v[216:217], v[200:201] op_sel_hi:[1,0]
	ds_read_b128 v[208:211], v2 offset:16384
	v_pk_fma_f32 v[164:165], v[74:75], v[176:177], v[164:165] op_sel:[0,1,0] op_sel_hi:[1,1,1]
	v_pk_mul_f32 v[220:221], v[216:217], v[200:201] op_sel:[0,1] op_sel_hi:[1,1]
	ds_read_b128 v[212:215], v2 offset:16400
	v_pk_fma_f32 v[164:165], v[76:77], v[178:179], v[164:165] op_sel_hi:[1,0,1]
	v_pk_mul_f32 v[222:223], v[216:217], v[202:203] op_sel_hi:[1,0]
	ds_read_b128 v[4:7], v2 offset:4352
	v_pk_fma_f32 v[164:165], v[78:79], v[178:179], v[164:165] op_sel:[0,1,0] op_sel_hi:[1,1,1]
	v_pk_mul_f32 v[224:225], v[216:217], v[202:203] op_sel:[0,1] op_sel_hi:[1,1]
	ds_read_b128 v[8:11], v2 offset:4368
	v_pk_fma_f32 v[164:165], v[80:81], v[180:181], v[164:165] op_sel_hi:[1,0,1]
	v_pk_mul_f32 v[226:227], v[216:217], v[204:205] op_sel_hi:[1,0]
	ds_read_b128 v[40:43], v2 offset:12544
	v_pk_fma_f32 v[164:165], v[82:83], v[180:181], v[164:165] op_sel:[0,1,0] op_sel_hi:[1,1,1]
	v_pk_mul_f32 v[228:229], v[216:217], v[204:205] op_sel:[0,1] op_sel_hi:[1,1]
	ds_read_b128 v[44:47], v2 offset:12560
	v_pk_fma_f32 v[164:165], v[84:85], v[182:183], v[164:165] op_sel_hi:[1,0,1]
	v_pk_mul_f32 v[230:231], v[216:217], v[206:207] op_sel_hi:[1,0]
	ds_read_b64 v[26:27], v3 offset:41216
	v_pk_fma_f32 v[164:165], v[86:87], v[182:183], v[164:165] op_sel:[0,1,0] op_sel_hi:[1,1,1]
	v_pk_mul_f32 v[234:235], v[216:217], v[206:207] op_sel:[0,1] op_sel_hi:[1,1]
	ds_read_b128 v[12:15], v2 offset:256
	v_pk_fma_f32 v[218:219], v[72:73], v[184:185], v[218:219] op_sel_hi:[1,0,1]
	v_pk_fma_f32 v[220:221], v[74:75], v[184:185], v[220:221] op_sel:[0,1,0] op_sel_hi:[1,1,1]
	ds_read_b128 v[28:31], v2 offset:272
	v_pk_fma_f32 v[222:223], v[76:77], v[186:187], v[222:223] op_sel_hi:[1,0,1]
	v_pk_fma_f32 v[224:225], v[78:79], v[186:187], v[224:225] op_sel:[0,1,0] op_sel_hi:[1,1,1]
	ds_read_b128 v[32:35], v2 offset:8448
	v_add_f32_dpp v164, v164, v164 quad_perm:[1,0,3,2] row_mask:0xf bank_mask:0xf bound_ctrl:1
	v_add_f32_dpp v165, v165, v165 quad_perm:[1,0,3,2] row_mask:0xf bank_mask:0xf bound_ctrl:1
	ds_read_b128 v[36:39], v2 offset:8464
	v_pk_fma_f32 v[226:227], v[80:81], v[188:189], v[226:227] op_sel_hi:[1,0,1]
	v_pk_fma_f32 v[228:229], v[82:83], v[188:189], v[228:229] op_sel:[0,1,0] op_sel_hi:[1,1,1]
	v_pk_fma_f32 v[230:231], v[84:85], v[190:191], v[230:231] op_sel_hi:[1,0,1]
	v_pk_fma_f32 v[234:235], v[86:87], v[190:191], v[234:235] op_sel:[0,1,0] op_sel_hi:[1,1,1]
	v_add_f32_dpp v164, v164, v164 quad_perm:[2,3,0,1] row_mask:0xf bank_mask:0xf bound_ctrl:1
	v_add_f32_dpp v165, v165, v165 quad_perm:[2,3,0,1] row_mask:0xf bank_mask:0xf bound_ctrl:1
	s_nop 0
	v_add_f32_dpp v164, v164, v164 row_half_mirror row_mask:0xf bank_mask:0xf bound_ctrl:1
	v_add_f32_dpp v165, v165, v165 row_half_mirror row_mask:0xf bank_mask:0xf bound_ctrl:1
	v_pk_fma_f32 v[72:73], v[192:193], v[164:165], v[218:219] op_sel_hi:[0,1,1]
	v_pk_fma_f32 v[74:75], v[192:193], v[164:165], v[220:221] op_sel:[1,0,0] op_sel_hi:[1,1,1]
	v_pk_fma_f32 v[76:77], v[194:195], v[164:165], v[222:223] op_sel_hi:[0,1,1]
	v_pk_fma_f32 v[78:79], v[194:195], v[164:165], v[224:225] op_sel:[1,0,0] op_sel_hi:[1,1,1]
	v_pk_fma_f32 v[80:81], v[196:197], v[164:165], v[226:227] op_sel_hi:[0,1,1]
	v_pk_fma_f32 v[82:83], v[196:197], v[164:165], v[228:229] op_sel:[1,0,0] op_sel_hi:[1,1,1]
	v_pk_fma_f32 v[84:85], v[198:199], v[164:165], v[230:231] op_sel_hi:[0,1,1]
	v_pk_fma_f32 v[86:87], v[198:199], v[164:165], v[234:235] op_sel:[1,0,0] op_sel_hi:[1,1,1]
	s_waitcnt lgkmcnt(0)
	v_pk_mul_f32 v[164:165], v[72:73], v[4:5] op_sel_hi:[1,0]
	v_pk_mul_f32 v[160:161], v[72:73], v[208:209] op_sel_hi:[1,0]
	ds_read_b128 v[48:51], v2 offset:16640
	v_pk_fma_f32 v[164:165], v[74:75], v[4:5], v[164:165] op_sel:[0,1,0] op_sel_hi:[1,1,1]
	v_pk_fma_f32 v[160:161], v[74:75], v[208:209], v[160:161] op_sel:[0,1,0] op_sel_hi:[1,1,1]
	ds_read_b128 v[52:55], v2 offset:16656
	v_pk_fma_f32 v[164:165], v[76:77], v[6:7], v[164:165] op_sel_hi:[1,0,1]
	v_pk_fma_f32 v[160:161], v[76:77], v[210:211], v[160:161] op_sel_hi:[1,0,1]
	ds_read_b128 v[176:179], v2 offset:4608
	v_pk_fma_f32 v[164:165], v[78:79], v[6:7], v[164:165] op_sel:[0,1,0] op_sel_hi:[1,1,1]
	v_pk_fma_f32 v[160:161], v[78:79], v[210:211], v[160:161] op_sel:[0,1,0] op_sel_hi:[1,1,1]
	ds_read_b128 v[180:183], v2 offset:4624
	v_pk_fma_f32 v[164:165], v[80:81], v[8:9], v[164:165] op_sel_hi:[1,0,1]
	v_pk_fma_f32 v[160:161], v[80:81], v[212:213], v[160:161] op_sel_hi:[1,0,1]
	ds_read_b128 v[200:203], v2 offset:12800
	v_pk_fma_f32 v[164:165], v[82:83], v[8:9], v[164:165] op_sel:[0,1,0] op_sel_hi:[1,1,1]
	v_pk_fma_f32 v[160:161], v[82:83], v[212:213], v[160:161] op_sel:[0,1,0] op_sel_hi:[1,1,1]
	ds_read_b128 v[204:207], v2 offset:12816
	v_pk_fma_f32 v[164:165], v[84:85], v[10:11], v[164:165] op_sel_hi:[1,0,1]
	v_pk_fma_f32 v[160:161], v[84:85], v[214:215], v[160:161] op_sel_hi:[1,0,1]
	ds_read_b64 v[216:217], v3 offset:41472
	v_pk_fma_f32 v[164:165], v[86:87], v[10:11], v[164:165] op_sel:[0,1,0] op_sel_hi:[1,1,1]
	v_pk_fma_f32 v[160:161], v[86:87], v[214:215], v[160:161] op_sel:[0,1,0] op_sel_hi:[1,1,1]
	ds_read_b128 v[184:187], v2 offset:512
	v_pk_mul_f32 v[218:219], v[26:27], v[40:41] op_sel_hi:[1,0]
	v_pk_mul_f32 v[220:221], v[26:27], v[40:41] op_sel:[0,1] op_sel_hi:[1,1]
	ds_read_b128 v[188:191], v2 offset:528
	v_pk_mul_f32 v[222:223], v[26:27], v[42:43] op_sel_hi:[1,0]
	v_pk_mul_f32 v[224:225], v[26:27], v[42:43] op_sel:[0,1] op_sel_hi:[1,1]
	ds_read_b128 v[192:195], v2 offset:8704
	v_pk_mul_f32 v[226:227], v[26:27], v[44:45] op_sel_hi:[1,0]
	v_pk_mul_f32 v[228:229], v[26:27], v[44:45] op_sel:[0,1] op_sel_hi:[1,1]
	ds_read_b128 v[196:199], v2 offset:8720
	v_pk_mul_f32 v[230:231], v[26:27], v[46:47] op_sel_hi:[1,0]
	v_pk_mul_f32 v[234:235], v[26:27], v[46:47] op_sel:[0,1] op_sel_hi:[1,1]
	v_pk_fma_f32 v[218:219], v[72:73], v[12:13], v[218:219] op_sel_hi:[1,0,1]
	v_pk_fma_f32 v[220:221], v[74:75], v[12:13], v[220:221] op_sel:[0,1,0] op_sel_hi:[1,1,1]
	v_pk_fma_f32 v[222:223], v[76:77], v[14:15], v[222:223] op_sel_hi:[1,0,1]
	v_pk_fma_f32 v[224:225], v[78:79], v[14:15], v[224:225] op_sel:[0,1,0] op_sel_hi:[1,1,1]
	v_add_f32_dpp v164, v164, v164 quad_perm:[1,0,3,2] row_mask:0xf bank_mask:0xf bound_ctrl:1
	v_add_f32_dpp v165, v165, v165 quad_perm:[1,0,3,2] row_mask:0xf bank_mask:0xf bound_ctrl:1
	v_add_f32_dpp v160, v160, v160 quad_perm:[1,0,3,2] row_mask:0xf bank_mask:0xf bound_ctrl:1
	v_add_f32_dpp v161, v161, v161 quad_perm:[1,0,3,2] row_mask:0xf bank_mask:0xf bound_ctrl:1
	v_pk_fma_f32 v[226:227], v[80:81], v[28:29], v[226:227] op_sel_hi:[1,0,1]
	v_pk_fma_f32 v[228:229], v[82:83], v[28:29], v[228:229] op_sel:[0,1,0] op_sel_hi:[1,1,1]
	v_pk_fma_f32 v[230:231], v[84:85], v[30:31], v[230:231] op_sel_hi:[1,0,1]
	v_pk_fma_f32 v[234:235], v[86:87], v[30:31], v[234:235] op_sel:[0,1,0] op_sel_hi:[1,1,1]
	v_add_f32_dpp v164, v164, v164 quad_perm:[2,3,0,1] row_mask:0xf bank_mask:0xf bound_ctrl:1
	v_add_f32_dpp v165, v165, v165 quad_perm:[2,3,0,1] row_mask:0xf bank_mask:0xf bound_ctrl:1
	v_add_f32_dpp v160, v160, v160 quad_perm:[2,3,0,1] row_mask:0xf bank_mask:0xf bound_ctrl:1
	v_add_f32_dpp v161, v161, v161 quad_perm:[2,3,0,1] row_mask:0xf bank_mask:0xf bound_ctrl:1
	v_add_f32_dpp v164, v164, v164 row_half_mirror row_mask:0xf bank_mask:0xf bound_ctrl:1
	v_add_f32_dpp v165, v165, v165 row_half_mirror row_mask:0xf bank_mask:0xf bound_ctrl:1
	v_add_f32_dpp v160, v160, v160 row_half_mirror row_mask:0xf bank_mask:0xf bound_ctrl:1
	v_add_f32_dpp v161, v161, v161 row_half_mirror row_mask:0xf bank_mask:0xf bound_ctrl:1
	v_pk_fma_f32 v[72:73], v[32:33], v[164:165], v[218:219] op_sel_hi:[0,1,1]
	v_pk_fma_f32 v[74:75], v[32:33], v[164:165], v[220:221] op_sel:[1,0,0] op_sel_hi:[1,1,1]
	v_pk_fma_f32 v[76:77], v[34:35], v[164:165], v[222:223] op_sel_hi:[0,1,1]
	v_pk_fma_f32 v[78:79], v[34:35], v[164:165], v[224:225] op_sel:[1,0,0] op_sel_hi:[1,1,1]
	v_pk_fma_f32 v[80:81], v[36:37], v[164:165], v[226:227] op_sel_hi:[0,1,1]
	v_pk_fma_f32 v[82:83], v[36:37], v[164:165], v[228:229] op_sel:[1,0,0] op_sel_hi:[1,1,1]
	v_pk_fma_f32 v[84:85], v[38:39], v[164:165], v[230:231] op_sel_hi:[0,1,1]
	v_pk_fma_f32 v[86:87], v[38:39], v[164:165], v[234:235] op_sel:[1,0,0] op_sel_hi:[1,1,1]
	ds_write_b64 v1, v[160:161] offset:54016
	s_waitcnt lgkmcnt(1)
	v_pk_mul_f32 v[164:165], v[72:73], v[176:177] op_sel_hi:[1,0]
	v_pk_mul_f32 v[160:161], v[72:73], v[48:49] op_sel_hi:[1,0]
	ds_read_b128 v[208:211], v2 offset:16896
	v_pk_fma_f32 v[164:165], v[74:75], v[176:177], v[164:165] op_sel:[0,1,0] op_sel_hi:[1,1,1]
	v_pk_fma_f32 v[160:161], v[74:75], v[48:49], v[160:161] op_sel:[0,1,0] op_sel_hi:[1,1,1]
	ds_read_b128 v[212:215], v2 offset:16912
	v_pk_fma_f32 v[164:165], v[76:77], v[178:179], v[164:165] op_sel_hi:[1,0,1]
	v_pk_fma_f32 v[160:161], v[76:77], v[50:51], v[160:161] op_sel_hi:[1,0,1]
	ds_read_b128 v[4:7], v2 offset:4864
	v_pk_fma_f32 v[164:165], v[78:79], v[178:179], v[164:165] op_sel:[0,1,0] op_sel_hi:[1,1,1]
	v_pk_fma_f32 v[160:161], v[78:79], v[50:51], v[160:161] op_sel:[0,1,0] op_sel_hi:[1,1,1]
	ds_read_b128 v[8:11], v2 offset:4880
	v_pk_fma_f32 v[164:165], v[80:81], v[180:181], v[164:165] op_sel_hi:[1,0,1]
	v_pk_fma_f32 v[160:161], v[80:81], v[52:53], v[160:161] op_sel_hi:[1,0,1]
	ds_read_b128 v[40:43], v2 offset:13056
	v_pk_fma_f32 v[164:165], v[82:83], v[180:181], v[164:165] op_sel:[0,1,0] op_sel_hi:[1,1,1]
	v_pk_fma_f32 v[160:161], v[82:83], v[52:53], v[160:161] op_sel:[0,1,0] op_sel_hi:[1,1,1]
	ds_read_b128 v[44:47], v2 offset:13072
	v_pk_fma_f32 v[164:165], v[84:85], v[182:183], v[164:165] op_sel_hi:[1,0,1]
	v_pk_fma_f32 v[160:161], v[84:85], v[54:55], v[160:161] op_sel_hi:[1,0,1]
	ds_read_b64 v[26:27], v3 offset:41728
	v_pk_fma_f32 v[164:165], v[86:87], v[182:183], v[164:165] op_sel:[0,1,0] op_sel_hi:[1,1,1]
	v_pk_fma_f32 v[160:161], v[86:87], v[54:55], v[160:161] op_sel:[0,1,0] op_sel_hi:[1,1,1]
	ds_read_b128 v[12:15], v2 offset:768
	v_pk_mul_f32 v[218:219], v[216:217], v[200:201] op_sel_hi:[1,0]
	v_pk_mul_f32 v[220:221], v[216:217], v[200:201] op_sel:[0,1] op_sel_hi:[1,1]
	ds_read_b128 v[28:31], v2 offset:784
	v_pk_mul_f32 v[222:223], v[216:217], v[202:203] op_sel_hi:[1,0]
	v_pk_mul_f32 v[224:225], v[216:217], v[202:203] op_sel:[0,1] op_sel_hi:[1,1]
	ds_read_b128 v[32:35], v2 offset:8960
	v_pk_mul_f32 v[226:227], v[216:217], v[204:205] op_sel_hi:[1,0]
	v_pk_mul_f32 v[228:229], v[216:217], v[204:205] op_sel:[0,1] op_sel_hi:[1,1]
	ds_read_b128 v[36:39], v2 offset:8976
	v_pk_mul_f32 v[230:231], v[216:217], v[206:207] op_sel_hi:[1,0]
	v_pk_mul_f32 v[234:235], v[216:217], v[206:207] op_sel:[0,1] op_sel_hi:[1,1]
	v_pk_fma_f32 v[218:219], v[72:73], v[184:185], v[218:219] op_sel_hi:[1,0,1]
	v_pk_fma_f32 v[220:221], v[74:75], v[184:185], v[220:221] op_sel:[0,1,0] op_sel_hi:[1,1,1]
	v_pk_fma_f32 v[222:223], v[76:77], v[186:187], v[222:223] op_sel_hi:[1,0,1]
	v_pk_fma_f32 v[224:225], v[78:79], v[186:187], v[224:225] op_sel:[0,1,0] op_sel_hi:[1,1,1]
	v_add_f32_dpp v164, v164, v164 quad_perm:[1,0,3,2] row_mask:0xf bank_mask:0xf bound_ctrl:1
	v_add_f32_dpp v165, v165, v165 quad_perm:[1,0,3,2] row_mask:0xf bank_mask:0xf bound_ctrl:1
	v_add_f32_dpp v160, v160, v160 quad_perm:[1,0,3,2] row_mask:0xf bank_mask:0xf bound_ctrl:1
	v_add_f32_dpp v161, v161, v161 quad_perm:[1,0,3,2] row_mask:0xf bank_mask:0xf bound_ctrl:1
	v_pk_fma_f32 v[226:227], v[80:81], v[188:189], v[226:227] op_sel_hi:[1,0,1]
	v_pk_fma_f32 v[228:229], v[82:83], v[188:189], v[228:229] op_sel:[0,1,0] op_sel_hi:[1,1,1]
	v_pk_fma_f32 v[230:231], v[84:85], v[190:191], v[230:231] op_sel_hi:[1,0,1]
	v_pk_fma_f32 v[234:235], v[86:87], v[190:191], v[234:235] op_sel:[0,1,0] op_sel_hi:[1,1,1]
	v_add_f32_dpp v164, v164, v164 quad_perm:[2,3,0,1] row_mask:0xf bank_mask:0xf bound_ctrl:1
	v_add_f32_dpp v165, v165, v165 quad_perm:[2,3,0,1] row_mask:0xf bank_mask:0xf bound_ctrl:1
	v_add_f32_dpp v160, v160, v160 quad_perm:[2,3,0,1] row_mask:0xf bank_mask:0xf bound_ctrl:1
	v_add_f32_dpp v161, v161, v161 quad_perm:[2,3,0,1] row_mask:0xf bank_mask:0xf bound_ctrl:1
	v_add_f32_dpp v164, v164, v164 row_half_mirror row_mask:0xf bank_mask:0xf bound_ctrl:1
	v_add_f32_dpp v165, v165, v165 row_half_mirror row_mask:0xf bank_mask:0xf bound_ctrl:1
	v_add_f32_dpp v160, v160, v160 row_half_mirror row_mask:0xf bank_mask:0xf bound_ctrl:1
	v_add_f32_dpp v161, v161, v161 row_half_mirror row_mask:0xf bank_mask:0xf bound_ctrl:1
	v_pk_fma_f32 v[72:73], v[192:193], v[164:165], v[218:219] op_sel_hi:[0,1,1]
	v_pk_fma_f32 v[74:75], v[192:193], v[164:165], v[220:221] op_sel:[1,0,0] op_sel_hi:[1,1,1]
	v_pk_fma_f32 v[76:77], v[194:195], v[164:165], v[222:223] op_sel_hi:[0,1,1]
	v_pk_fma_f32 v[78:79], v[194:195], v[164:165], v[224:225] op_sel:[1,0,0] op_sel_hi:[1,1,1]
	v_pk_fma_f32 v[80:81], v[196:197], v[164:165], v[226:227] op_sel_hi:[0,1,1]
	v_pk_fma_f32 v[82:83], v[196:197], v[164:165], v[228:229] op_sel:[1,0,0] op_sel_hi:[1,1,1]
	v_pk_fma_f32 v[84:85], v[198:199], v[164:165], v[230:231] op_sel_hi:[0,1,1]
	v_pk_fma_f32 v[86:87], v[198:199], v[164:165], v[234:235] op_sel:[1,0,0] op_sel_hi:[1,1,1]
	ds_write_b64 v1, v[160:161] offset:54272
	s_waitcnt lgkmcnt(1)
	v_pk_mul_f32 v[164:165], v[72:73], v[4:5] op_sel_hi:[1,0]
	v_pk_mul_f32 v[160:161], v[72:73], v[208:209] op_sel_hi:[1,0]
	ds_read_b128 v[48:51], v2 offset:17152
	v_pk_fma_f32 v[164:165], v[74:75], v[4:5], v[164:165] op_sel:[0,1,0] op_sel_hi:[1,1,1]
	v_pk_fma_f32 v[160:161], v[74:75], v[208:209], v[160:161] op_sel:[0,1,0] op_sel_hi:[1,1,1]
	ds_read_b128 v[52:55], v2 offset:17168
	v_pk_fma_f32 v[164:165], v[76:77], v[6:7], v[164:165] op_sel_hi:[1,0,1]
	v_pk_fma_f32 v[160:161], v[76:77], v[210:211], v[160:161] op_sel_hi:[1,0,1]
	ds_read_b128 v[176:179], v2 offset:5120
	v_pk_fma_f32 v[164:165], v[78:79], v[6:7], v[164:165] op_sel:[0,1,0] op_sel_hi:[1,1,1]
	v_pk_fma_f32 v[160:161], v[78:79], v[210:211], v[160:161] op_sel:[0,1,0] op_sel_hi:[1,1,1]
	ds_read_b128 v[180:183], v2 offset:5136
	v_pk_fma_f32 v[164:165], v[80:81], v[8:9], v[164:165] op_sel_hi:[1,0,1]
	v_pk_fma_f32 v[160:161], v[80:81], v[212:213], v[160:161] op_sel_hi:[1,0,1]
	ds_read_b128 v[200:203], v2 offset:13312
	v_pk_fma_f32 v[164:165], v[82:83], v[8:9], v[164:165] op_sel:[0,1,0] op_sel_hi:[1,1,1]
	v_pk_fma_f32 v[160:161], v[82:83], v[212:213], v[160:161] op_sel:[0,1,0] op_sel_hi:[1,1,1]
	ds_read_b128 v[204:207], v2 offset:13328
	v_pk_fma_f32 v[164:165], v[84:85], v[10:11], v[164:165] op_sel_hi:[1,0,1]
	v_pk_fma_f32 v[160:161], v[84:85], v[214:215], v[160:161] op_sel_hi:[1,0,1]
	ds_read_b64 v[216:217], v3 offset:41984
	v_pk_fma_f32 v[164:165], v[86:87], v[10:11], v[164:165] op_sel:[0,1,0] op_sel_hi:[1,1,1]
	v_pk_fma_f32 v[160:161], v[86:87], v[214:215], v[160:161] op_sel:[0,1,0] op_sel_hi:[1,1,1]
	ds_read_b128 v[184:187], v2 offset:1024
	v_pk_mul_f32 v[218:219], v[26:27], v[40:41] op_sel_hi:[1,0]
	v_pk_mul_f32 v[220:221], v[26:27], v[40:41] op_sel:[0,1] op_sel_hi:[1,1]
	ds_read_b128 v[188:191], v2 offset:1040
	v_pk_mul_f32 v[222:223], v[26:27], v[42:43] op_sel_hi:[1,0]
	v_pk_mul_f32 v[224:225], v[26:27], v[42:43] op_sel:[0,1] op_sel_hi:[1,1]
	ds_read_b128 v[192:195], v2 offset:9216
	v_pk_mul_f32 v[226:227], v[26:27], v[44:45] op_sel_hi:[1,0]
	v_pk_mul_f32 v[228:229], v[26:27], v[44:45] op_sel:[0,1] op_sel_hi:[1,1]
	ds_read_b128 v[196:199], v2 offset:9232
	v_pk_mul_f32 v[230:231], v[26:27], v[46:47] op_sel_hi:[1,0]
	v_pk_mul_f32 v[234:235], v[26:27], v[46:47] op_sel:[0,1] op_sel_hi:[1,1]
	v_pk_fma_f32 v[218:219], v[72:73], v[12:13], v[218:219] op_sel_hi:[1,0,1]
	v_pk_fma_f32 v[220:221], v[74:75], v[12:13], v[220:221] op_sel:[0,1,0] op_sel_hi:[1,1,1]
	v_pk_fma_f32 v[222:223], v[76:77], v[14:15], v[222:223] op_sel_hi:[1,0,1]
	v_pk_fma_f32 v[224:225], v[78:79], v[14:15], v[224:225] op_sel:[0,1,0] op_sel_hi:[1,1,1]
	v_add_f32_dpp v164, v164, v164 quad_perm:[1,0,3,2] row_mask:0xf bank_mask:0xf bound_ctrl:1
	v_add_f32_dpp v165, v165, v165 quad_perm:[1,0,3,2] row_mask:0xf bank_mask:0xf bound_ctrl:1
	v_add_f32_dpp v160, v160, v160 quad_perm:[1,0,3,2] row_mask:0xf bank_mask:0xf bound_ctrl:1
	v_add_f32_dpp v161, v161, v161 quad_perm:[1,0,3,2] row_mask:0xf bank_mask:0xf bound_ctrl:1
	v_pk_fma_f32 v[226:227], v[80:81], v[28:29], v[226:227] op_sel_hi:[1,0,1]
	v_pk_fma_f32 v[228:229], v[82:83], v[28:29], v[228:229] op_sel:[0,1,0] op_sel_hi:[1,1,1]
	v_pk_fma_f32 v[230:231], v[84:85], v[30:31], v[230:231] op_sel_hi:[1,0,1]
	v_pk_fma_f32 v[234:235], v[86:87], v[30:31], v[234:235] op_sel:[0,1,0] op_sel_hi:[1,1,1]
	v_add_f32_dpp v164, v164, v164 quad_perm:[2,3,0,1] row_mask:0xf bank_mask:0xf bound_ctrl:1
	v_add_f32_dpp v165, v165, v165 quad_perm:[2,3,0,1] row_mask:0xf bank_mask:0xf bound_ctrl:1
	v_add_f32_dpp v160, v160, v160 quad_perm:[2,3,0,1] row_mask:0xf bank_mask:0xf bound_ctrl:1
	v_add_f32_dpp v161, v161, v161 quad_perm:[2,3,0,1] row_mask:0xf bank_mask:0xf bound_ctrl:1
	v_add_f32_dpp v164, v164, v164 row_half_mirror row_mask:0xf bank_mask:0xf bound_ctrl:1
	v_add_f32_dpp v165, v165, v165 row_half_mirror row_mask:0xf bank_mask:0xf bound_ctrl:1
	v_add_f32_dpp v160, v160, v160 row_half_mirror row_mask:0xf bank_mask:0xf bound_ctrl:1
	v_add_f32_dpp v161, v161, v161 row_half_mirror row_mask:0xf bank_mask:0xf bound_ctrl:1
	v_pk_fma_f32 v[72:73], v[32:33], v[164:165], v[218:219] op_sel_hi:[0,1,1]
	v_pk_fma_f32 v[74:75], v[32:33], v[164:165], v[220:221] op_sel:[1,0,0] op_sel_hi:[1,1,1]
	v_pk_fma_f32 v[76:77], v[34:35], v[164:165], v[222:223] op_sel_hi:[0,1,1]
	v_pk_fma_f32 v[78:79], v[34:35], v[164:165], v[224:225] op_sel:[1,0,0] op_sel_hi:[1,1,1]
	v_pk_fma_f32 v[80:81], v[36:37], v[164:165], v[226:227] op_sel_hi:[0,1,1]
	v_pk_fma_f32 v[82:83], v[36:37], v[164:165], v[228:229] op_sel:[1,0,0] op_sel_hi:[1,1,1]
	v_pk_fma_f32 v[84:85], v[38:39], v[164:165], v[230:231] op_sel_hi:[0,1,1]
	v_pk_fma_f32 v[86:87], v[38:39], v[164:165], v[234:235] op_sel:[1,0,0] op_sel_hi:[1,1,1]
	ds_write_b64 v1, v[160:161] offset:54528
	s_waitcnt lgkmcnt(1)
	v_pk_mul_f32 v[164:165], v[72:73], v[176:177] op_sel_hi:[1,0]
	v_pk_mul_f32 v[160:161], v[72:73], v[48:49] op_sel_hi:[1,0]
	ds_read_b128 v[208:211], v2 offset:17408
	v_pk_fma_f32 v[164:165], v[74:75], v[176:177], v[164:165] op_sel:[0,1,0] op_sel_hi:[1,1,1]
	v_pk_fma_f32 v[160:161], v[74:75], v[48:49], v[160:161] op_sel:[0,1,0] op_sel_hi:[1,1,1]
	ds_read_b128 v[212:215], v2 offset:17424
	v_pk_fma_f32 v[164:165], v[76:77], v[178:179], v[164:165] op_sel_hi:[1,0,1]
	v_pk_fma_f32 v[160:161], v[76:77], v[50:51], v[160:161] op_sel_hi:[1,0,1]
	ds_read_b128 v[4:7], v2 offset:5376
	v_pk_fma_f32 v[164:165], v[78:79], v[178:179], v[164:165] op_sel:[0,1,0] op_sel_hi:[1,1,1]
	v_pk_fma_f32 v[160:161], v[78:79], v[50:51], v[160:161] op_sel:[0,1,0] op_sel_hi:[1,1,1]
	ds_read_b128 v[8:11], v2 offset:5392
	v_pk_fma_f32 v[164:165], v[80:81], v[180:181], v[164:165] op_sel_hi:[1,0,1]
	v_pk_fma_f32 v[160:161], v[80:81], v[52:53], v[160:161] op_sel_hi:[1,0,1]
	ds_read_b128 v[40:43], v2 offset:13568
	v_pk_fma_f32 v[164:165], v[82:83], v[180:181], v[164:165] op_sel:[0,1,0] op_sel_hi:[1,1,1]
	v_pk_fma_f32 v[160:161], v[82:83], v[52:53], v[160:161] op_sel:[0,1,0] op_sel_hi:[1,1,1]
	ds_read_b128 v[44:47], v2 offset:13584
	v_pk_fma_f32 v[164:165], v[84:85], v[182:183], v[164:165] op_sel_hi:[1,0,1]
	v_pk_fma_f32 v[160:161], v[84:85], v[54:55], v[160:161] op_sel_hi:[1,0,1]
	ds_read_b64 v[26:27], v3 offset:42240
	v_pk_fma_f32 v[164:165], v[86:87], v[182:183], v[164:165] op_sel:[0,1,0] op_sel_hi:[1,1,1]
	v_pk_fma_f32 v[160:161], v[86:87], v[54:55], v[160:161] op_sel:[0,1,0] op_sel_hi:[1,1,1]
	ds_read_b128 v[12:15], v2 offset:1280
	v_pk_mul_f32 v[218:219], v[216:217], v[200:201] op_sel_hi:[1,0]
	v_pk_mul_f32 v[220:221], v[216:217], v[200:201] op_sel:[0,1] op_sel_hi:[1,1]
	ds_read_b128 v[28:31], v2 offset:1296
	v_pk_mul_f32 v[222:223], v[216:217], v[202:203] op_sel_hi:[1,0]
	v_pk_mul_f32 v[224:225], v[216:217], v[202:203] op_sel:[0,1] op_sel_hi:[1,1]
	ds_read_b128 v[32:35], v2 offset:9472
	v_pk_mul_f32 v[226:227], v[216:217], v[204:205] op_sel_hi:[1,0]
	v_pk_mul_f32 v[228:229], v[216:217], v[204:205] op_sel:[0,1] op_sel_hi:[1,1]
	ds_read_b128 v[36:39], v2 offset:9488
	v_pk_mul_f32 v[230:231], v[216:217], v[206:207] op_sel_hi:[1,0]
	v_pk_mul_f32 v[234:235], v[216:217], v[206:207] op_sel:[0,1] op_sel_hi:[1,1]
	v_pk_fma_f32 v[218:219], v[72:73], v[184:185], v[218:219] op_sel_hi:[1,0,1]
	v_pk_fma_f32 v[220:221], v[74:75], v[184:185], v[220:221] op_sel:[0,1,0] op_sel_hi:[1,1,1]
	v_pk_fma_f32 v[222:223], v[76:77], v[186:187], v[222:223] op_sel_hi:[1,0,1]
	v_pk_fma_f32 v[224:225], v[78:79], v[186:187], v[224:225] op_sel:[0,1,0] op_sel_hi:[1,1,1]
	v_add_f32_dpp v164, v164, v164 quad_perm:[1,0,3,2] row_mask:0xf bank_mask:0xf bound_ctrl:1
	v_add_f32_dpp v165, v165, v165 quad_perm:[1,0,3,2] row_mask:0xf bank_mask:0xf bound_ctrl:1
	v_add_f32_dpp v160, v160, v160 quad_perm:[1,0,3,2] row_mask:0xf bank_mask:0xf bound_ctrl:1
	v_add_f32_dpp v161, v161, v161 quad_perm:[1,0,3,2] row_mask:0xf bank_mask:0xf bound_ctrl:1
	v_pk_fma_f32 v[226:227], v[80:81], v[188:189], v[226:227] op_sel_hi:[1,0,1]
	v_pk_fma_f32 v[228:229], v[82:83], v[188:189], v[228:229] op_sel:[0,1,0] op_sel_hi:[1,1,1]
	v_pk_fma_f32 v[230:231], v[84:85], v[190:191], v[230:231] op_sel_hi:[1,0,1]
	v_pk_fma_f32 v[234:235], v[86:87], v[190:191], v[234:235] op_sel:[0,1,0] op_sel_hi:[1,1,1]
	v_add_f32_dpp v164, v164, v164 quad_perm:[2,3,0,1] row_mask:0xf bank_mask:0xf bound_ctrl:1
	v_add_f32_dpp v165, v165, v165 quad_perm:[2,3,0,1] row_mask:0xf bank_mask:0xf bound_ctrl:1
	v_add_f32_dpp v160, v160, v160 quad_perm:[2,3,0,1] row_mask:0xf bank_mask:0xf bound_ctrl:1
	v_add_f32_dpp v161, v161, v161 quad_perm:[2,3,0,1] row_mask:0xf bank_mask:0xf bound_ctrl:1
	v_add_f32_dpp v164, v164, v164 row_half_mirror row_mask:0xf bank_mask:0xf bound_ctrl:1
	v_add_f32_dpp v165, v165, v165 row_half_mirror row_mask:0xf bank_mask:0xf bound_ctrl:1
	v_add_f32_dpp v160, v160, v160 row_half_mirror row_mask:0xf bank_mask:0xf bound_ctrl:1
	v_add_f32_dpp v161, v161, v161 row_half_mirror row_mask:0xf bank_mask:0xf bound_ctrl:1
	v_pk_fma_f32 v[72:73], v[192:193], v[164:165], v[218:219] op_sel_hi:[0,1,1]
	v_pk_fma_f32 v[74:75], v[192:193], v[164:165], v[220:221] op_sel:[1,0,0] op_sel_hi:[1,1,1]
	v_pk_fma_f32 v[76:77], v[194:195], v[164:165], v[222:223] op_sel_hi:[0,1,1]
	v_pk_fma_f32 v[78:79], v[194:195], v[164:165], v[224:225] op_sel:[1,0,0] op_sel_hi:[1,1,1]
	v_pk_fma_f32 v[80:81], v[196:197], v[164:165], v[226:227] op_sel_hi:[0,1,1]
	v_pk_fma_f32 v[82:83], v[196:197], v[164:165], v[228:229] op_sel:[1,0,0] op_sel_hi:[1,1,1]
	v_pk_fma_f32 v[84:85], v[198:199], v[164:165], v[230:231] op_sel_hi:[0,1,1]
	v_pk_fma_f32 v[86:87], v[198:199], v[164:165], v[234:235] op_sel:[1,0,0] op_sel_hi:[1,1,1]
	ds_write_b64 v1, v[160:161] offset:54784
	s_waitcnt lgkmcnt(1)
	v_pk_mul_f32 v[164:165], v[72:73], v[4:5] op_sel_hi:[1,0]
	v_pk_mul_f32 v[160:161], v[72:73], v[208:209] op_sel_hi:[1,0]
	ds_read_b128 v[48:51], v2 offset:17664
	v_pk_fma_f32 v[164:165], v[74:75], v[4:5], v[164:165] op_sel:[0,1,0] op_sel_hi:[1,1,1]
	v_pk_fma_f32 v[160:161], v[74:75], v[208:209], v[160:161] op_sel:[0,1,0] op_sel_hi:[1,1,1]
	ds_read_b128 v[52:55], v2 offset:17680
	v_pk_fma_f32 v[164:165], v[76:77], v[6:7], v[164:165] op_sel_hi:[1,0,1]
	v_pk_fma_f32 v[160:161], v[76:77], v[210:211], v[160:161] op_sel_hi:[1,0,1]
	ds_read_b128 v[176:179], v2 offset:5632
	v_pk_fma_f32 v[164:165], v[78:79], v[6:7], v[164:165] op_sel:[0,1,0] op_sel_hi:[1,1,1]
	v_pk_fma_f32 v[160:161], v[78:79], v[210:211], v[160:161] op_sel:[0,1,0] op_sel_hi:[1,1,1]
	ds_read_b128 v[180:183], v2 offset:5648
	v_pk_fma_f32 v[164:165], v[80:81], v[8:9], v[164:165] op_sel_hi:[1,0,1]
	v_pk_fma_f32 v[160:161], v[80:81], v[212:213], v[160:161] op_sel_hi:[1,0,1]
	ds_read_b128 v[200:203], v2 offset:13824
	v_pk_fma_f32 v[164:165], v[82:83], v[8:9], v[164:165] op_sel:[0,1,0] op_sel_hi:[1,1,1]
	v_pk_fma_f32 v[160:161], v[82:83], v[212:213], v[160:161] op_sel:[0,1,0] op_sel_hi:[1,1,1]
	ds_read_b128 v[204:207], v2 offset:13840
	v_pk_fma_f32 v[164:165], v[84:85], v[10:11], v[164:165] op_sel_hi:[1,0,1]
	v_pk_fma_f32 v[160:161], v[84:85], v[214:215], v[160:161] op_sel_hi:[1,0,1]
	ds_read_b64 v[216:217], v3 offset:42496
	v_pk_fma_f32 v[164:165], v[86:87], v[10:11], v[164:165] op_sel:[0,1,0] op_sel_hi:[1,1,1]
	v_pk_fma_f32 v[160:161], v[86:87], v[214:215], v[160:161] op_sel:[0,1,0] op_sel_hi:[1,1,1]
	ds_read_b128 v[184:187], v2 offset:1536
	v_pk_mul_f32 v[218:219], v[26:27], v[40:41] op_sel_hi:[1,0]
	v_pk_mul_f32 v[220:221], v[26:27], v[40:41] op_sel:[0,1] op_sel_hi:[1,1]
	ds_read_b128 v[188:191], v2 offset:1552
	v_pk_mul_f32 v[222:223], v[26:27], v[42:43] op_sel_hi:[1,0]
	v_pk_mul_f32 v[224:225], v[26:27], v[42:43] op_sel:[0,1] op_sel_hi:[1,1]
	ds_read_b128 v[192:195], v2 offset:9728
	v_pk_mul_f32 v[226:227], v[26:27], v[44:45] op_sel_hi:[1,0]
	v_pk_mul_f32 v[228:229], v[26:27], v[44:45] op_sel:[0,1] op_sel_hi:[1,1]
	ds_read_b128 v[196:199], v2 offset:9744
	v_pk_mul_f32 v[230:231], v[26:27], v[46:47] op_sel_hi:[1,0]
	v_pk_mul_f32 v[234:235], v[26:27], v[46:47] op_sel:[0,1] op_sel_hi:[1,1]
	v_pk_fma_f32 v[218:219], v[72:73], v[12:13], v[218:219] op_sel_hi:[1,0,1]
	v_pk_fma_f32 v[220:221], v[74:75], v[12:13], v[220:221] op_sel:[0,1,0] op_sel_hi:[1,1,1]
	v_pk_fma_f32 v[222:223], v[76:77], v[14:15], v[222:223] op_sel_hi:[1,0,1]
	v_pk_fma_f32 v[224:225], v[78:79], v[14:15], v[224:225] op_sel:[0,1,0] op_sel_hi:[1,1,1]
	v_add_f32_dpp v164, v164, v164 quad_perm:[1,0,3,2] row_mask:0xf bank_mask:0xf bound_ctrl:1
	v_add_f32_dpp v165, v165, v165 quad_perm:[1,0,3,2] row_mask:0xf bank_mask:0xf bound_ctrl:1
	v_add_f32_dpp v160, v160, v160 quad_perm:[1,0,3,2] row_mask:0xf bank_mask:0xf bound_ctrl:1
	v_add_f32_dpp v161, v161, v161 quad_perm:[1,0,3,2] row_mask:0xf bank_mask:0xf bound_ctrl:1
	v_pk_fma_f32 v[226:227], v[80:81], v[28:29], v[226:227] op_sel_hi:[1,0,1]
	v_pk_fma_f32 v[228:229], v[82:83], v[28:29], v[228:229] op_sel:[0,1,0] op_sel_hi:[1,1,1]
	v_pk_fma_f32 v[230:231], v[84:85], v[30:31], v[230:231] op_sel_hi:[1,0,1]
	v_pk_fma_f32 v[234:235], v[86:87], v[30:31], v[234:235] op_sel:[0,1,0] op_sel_hi:[1,1,1]
	v_add_f32_dpp v164, v164, v164 quad_perm:[2,3,0,1] row_mask:0xf bank_mask:0xf bound_ctrl:1
	v_add_f32_dpp v165, v165, v165 quad_perm:[2,3,0,1] row_mask:0xf bank_mask:0xf bound_ctrl:1
	v_add_f32_dpp v160, v160, v160 quad_perm:[2,3,0,1] row_mask:0xf bank_mask:0xf bound_ctrl:1
	v_add_f32_dpp v161, v161, v161 quad_perm:[2,3,0,1] row_mask:0xf bank_mask:0xf bound_ctrl:1
	v_add_f32_dpp v164, v164, v164 row_half_mirror row_mask:0xf bank_mask:0xf bound_ctrl:1
	v_add_f32_dpp v165, v165, v165 row_half_mirror row_mask:0xf bank_mask:0xf bound_ctrl:1
	v_add_f32_dpp v160, v160, v160 row_half_mirror row_mask:0xf bank_mask:0xf bound_ctrl:1
	v_add_f32_dpp v161, v161, v161 row_half_mirror row_mask:0xf bank_mask:0xf bound_ctrl:1
	v_pk_fma_f32 v[72:73], v[32:33], v[164:165], v[218:219] op_sel_hi:[0,1,1]
	v_pk_fma_f32 v[74:75], v[32:33], v[164:165], v[220:221] op_sel:[1,0,0] op_sel_hi:[1,1,1]
	v_pk_fma_f32 v[76:77], v[34:35], v[164:165], v[222:223] op_sel_hi:[0,1,1]
	v_pk_fma_f32 v[78:79], v[34:35], v[164:165], v[224:225] op_sel:[1,0,0] op_sel_hi:[1,1,1]
	v_pk_fma_f32 v[80:81], v[36:37], v[164:165], v[226:227] op_sel_hi:[0,1,1]
	v_pk_fma_f32 v[82:83], v[36:37], v[164:165], v[228:229] op_sel:[1,0,0] op_sel_hi:[1,1,1]
	v_pk_fma_f32 v[84:85], v[38:39], v[164:165], v[230:231] op_sel_hi:[0,1,1]
	v_pk_fma_f32 v[86:87], v[38:39], v[164:165], v[234:235] op_sel:[1,0,0] op_sel_hi:[1,1,1]
	ds_write_b64 v1, v[160:161] offset:55040
	s_waitcnt lgkmcnt(1)
	v_pk_mul_f32 v[164:165], v[72:73], v[176:177] op_sel_hi:[1,0]
	v_pk_mul_f32 v[160:161], v[72:73], v[48:49] op_sel_hi:[1,0]
	ds_read_b128 v[208:211], v2 offset:17920
	v_pk_fma_f32 v[164:165], v[74:75], v[176:177], v[164:165] op_sel:[0,1,0] op_sel_hi:[1,1,1]
	v_pk_fma_f32 v[160:161], v[74:75], v[48:49], v[160:161] op_sel:[0,1,0] op_sel_hi:[1,1,1]
	ds_read_b128 v[212:215], v2 offset:17936
	v_pk_fma_f32 v[164:165], v[76:77], v[178:179], v[164:165] op_sel_hi:[1,0,1]
	v_pk_fma_f32 v[160:161], v[76:77], v[50:51], v[160:161] op_sel_hi:[1,0,1]
	ds_read_b128 v[4:7], v2 offset:5888
	v_pk_fma_f32 v[164:165], v[78:79], v[178:179], v[164:165] op_sel:[0,1,0] op_sel_hi:[1,1,1]
	v_pk_fma_f32 v[160:161], v[78:79], v[50:51], v[160:161] op_sel:[0,1,0] op_sel_hi:[1,1,1]
	ds_read_b128 v[8:11], v2 offset:5904
	v_pk_fma_f32 v[164:165], v[80:81], v[180:181], v[164:165] op_sel_hi:[1,0,1]
	v_pk_fma_f32 v[160:161], v[80:81], v[52:53], v[160:161] op_sel_hi:[1,0,1]
	ds_read_b128 v[40:43], v2 offset:14080
	v_pk_fma_f32 v[164:165], v[82:83], v[180:181], v[164:165] op_sel:[0,1,0] op_sel_hi:[1,1,1]
	v_pk_fma_f32 v[160:161], v[82:83], v[52:53], v[160:161] op_sel:[0,1,0] op_sel_hi:[1,1,1]
	ds_read_b128 v[44:47], v2 offset:14096
	v_pk_fma_f32 v[164:165], v[84:85], v[182:183], v[164:165] op_sel_hi:[1,0,1]
	v_pk_fma_f32 v[160:161], v[84:85], v[54:55], v[160:161] op_sel_hi:[1,0,1]
	ds_read_b64 v[26:27], v3 offset:42752
	v_pk_fma_f32 v[164:165], v[86:87], v[182:183], v[164:165] op_sel:[0,1,0] op_sel_hi:[1,1,1]
	v_pk_fma_f32 v[160:161], v[86:87], v[54:55], v[160:161] op_sel:[0,1,0] op_sel_hi:[1,1,1]
	ds_read_b128 v[12:15], v2 offset:1792
	v_pk_mul_f32 v[218:219], v[216:217], v[200:201] op_sel_hi:[1,0]
	v_pk_mul_f32 v[220:221], v[216:217], v[200:201] op_sel:[0,1] op_sel_hi:[1,1]
	ds_read_b128 v[28:31], v2 offset:1808
	v_pk_mul_f32 v[222:223], v[216:217], v[202:203] op_sel_hi:[1,0]
	v_pk_mul_f32 v[224:225], v[216:217], v[202:203] op_sel:[0,1] op_sel_hi:[1,1]
	ds_read_b128 v[32:35], v2 offset:9984
	v_pk_mul_f32 v[226:227], v[216:217], v[204:205] op_sel_hi:[1,0]
	v_pk_mul_f32 v[228:229], v[216:217], v[204:205] op_sel:[0,1] op_sel_hi:[1,1]
	ds_read_b128 v[36:39], v2 offset:10000
	v_pk_mul_f32 v[230:231], v[216:217], v[206:207] op_sel_hi:[1,0]
	v_pk_mul_f32 v[234:235], v[216:217], v[206:207] op_sel:[0,1] op_sel_hi:[1,1]
	v_pk_fma_f32 v[218:219], v[72:73], v[184:185], v[218:219] op_sel_hi:[1,0,1]
	v_pk_fma_f32 v[220:221], v[74:75], v[184:185], v[220:221] op_sel:[0,1,0] op_sel_hi:[1,1,1]
	v_pk_fma_f32 v[222:223], v[76:77], v[186:187], v[222:223] op_sel_hi:[1,0,1]
	v_pk_fma_f32 v[224:225], v[78:79], v[186:187], v[224:225] op_sel:[0,1,0] op_sel_hi:[1,1,1]
	v_add_f32_dpp v164, v164, v164 quad_perm:[1,0,3,2] row_mask:0xf bank_mask:0xf bound_ctrl:1
	v_add_f32_dpp v165, v165, v165 quad_perm:[1,0,3,2] row_mask:0xf bank_mask:0xf bound_ctrl:1
	v_add_f32_dpp v160, v160, v160 quad_perm:[1,0,3,2] row_mask:0xf bank_mask:0xf bound_ctrl:1
	v_add_f32_dpp v161, v161, v161 quad_perm:[1,0,3,2] row_mask:0xf bank_mask:0xf bound_ctrl:1
	v_pk_fma_f32 v[226:227], v[80:81], v[188:189], v[226:227] op_sel_hi:[1,0,1]
	v_pk_fma_f32 v[228:229], v[82:83], v[188:189], v[228:229] op_sel:[0,1,0] op_sel_hi:[1,1,1]
	v_pk_fma_f32 v[230:231], v[84:85], v[190:191], v[230:231] op_sel_hi:[1,0,1]
	v_pk_fma_f32 v[234:235], v[86:87], v[190:191], v[234:235] op_sel:[0,1,0] op_sel_hi:[1,1,1]
	v_add_f32_dpp v164, v164, v164 quad_perm:[2,3,0,1] row_mask:0xf bank_mask:0xf bound_ctrl:1
	v_add_f32_dpp v165, v165, v165 quad_perm:[2,3,0,1] row_mask:0xf bank_mask:0xf bound_ctrl:1
	v_add_f32_dpp v160, v160, v160 quad_perm:[2,3,0,1] row_mask:0xf bank_mask:0xf bound_ctrl:1
	v_add_f32_dpp v161, v161, v161 quad_perm:[2,3,0,1] row_mask:0xf bank_mask:0xf bound_ctrl:1
	v_add_f32_dpp v164, v164, v164 row_half_mirror row_mask:0xf bank_mask:0xf bound_ctrl:1
	v_add_f32_dpp v165, v165, v165 row_half_mirror row_mask:0xf bank_mask:0xf bound_ctrl:1
	v_add_f32_dpp v160, v160, v160 row_half_mirror row_mask:0xf bank_mask:0xf bound_ctrl:1
	v_add_f32_dpp v161, v161, v161 row_half_mirror row_mask:0xf bank_mask:0xf bound_ctrl:1
	v_pk_fma_f32 v[72:73], v[192:193], v[164:165], v[218:219] op_sel_hi:[0,1,1]
	v_pk_fma_f32 v[74:75], v[192:193], v[164:165], v[220:221] op_sel:[1,0,0] op_sel_hi:[1,1,1]
	v_pk_fma_f32 v[76:77], v[194:195], v[164:165], v[222:223] op_sel_hi:[0,1,1]
	v_pk_fma_f32 v[78:79], v[194:195], v[164:165], v[224:225] op_sel:[1,0,0] op_sel_hi:[1,1,1]
	v_pk_fma_f32 v[80:81], v[196:197], v[164:165], v[226:227] op_sel_hi:[0,1,1]
	v_pk_fma_f32 v[82:83], v[196:197], v[164:165], v[228:229] op_sel:[1,0,0] op_sel_hi:[1,1,1]
	v_pk_fma_f32 v[84:85], v[198:199], v[164:165], v[230:231] op_sel_hi:[0,1,1]
	v_pk_fma_f32 v[86:87], v[198:199], v[164:165], v[234:235] op_sel:[1,0,0] op_sel_hi:[1,1,1]
	ds_write_b64 v1, v[160:161] offset:55296
	s_waitcnt lgkmcnt(1)
	v_pk_mul_f32 v[164:165], v[72:73], v[4:5] op_sel_hi:[1,0]
	v_pk_mul_f32 v[160:161], v[72:73], v[208:209] op_sel_hi:[1,0]
	ds_read_b128 v[48:51], v2 offset:18176
	v_pk_fma_f32 v[164:165], v[74:75], v[4:5], v[164:165] op_sel:[0,1,0] op_sel_hi:[1,1,1]
	v_pk_fma_f32 v[160:161], v[74:75], v[208:209], v[160:161] op_sel:[0,1,0] op_sel_hi:[1,1,1]
	ds_read_b128 v[52:55], v2 offset:18192
	v_pk_fma_f32 v[164:165], v[76:77], v[6:7], v[164:165] op_sel_hi:[1,0,1]
	v_pk_fma_f32 v[160:161], v[76:77], v[210:211], v[160:161] op_sel_hi:[1,0,1]
	ds_read_b128 v[176:179], v2 offset:6144
	v_pk_fma_f32 v[164:165], v[78:79], v[6:7], v[164:165] op_sel:[0,1,0] op_sel_hi:[1,1,1]
	v_pk_fma_f32 v[160:161], v[78:79], v[210:211], v[160:161] op_sel:[0,1,0] op_sel_hi:[1,1,1]
	ds_read_b128 v[180:183], v2 offset:6160
	v_pk_fma_f32 v[164:165], v[80:81], v[8:9], v[164:165] op_sel_hi:[1,0,1]
	v_pk_fma_f32 v[160:161], v[80:81], v[212:213], v[160:161] op_sel_hi:[1,0,1]
	ds_read_b128 v[200:203], v2 offset:14336
	v_pk_fma_f32 v[164:165], v[82:83], v[8:9], v[164:165] op_sel:[0,1,0] op_sel_hi:[1,1,1]
	v_pk_fma_f32 v[160:161], v[82:83], v[212:213], v[160:161] op_sel:[0,1,0] op_sel_hi:[1,1,1]
	ds_read_b128 v[204:207], v2 offset:14352
	v_pk_fma_f32 v[164:165], v[84:85], v[10:11], v[164:165] op_sel_hi:[1,0,1]
	v_pk_fma_f32 v[160:161], v[84:85], v[214:215], v[160:161] op_sel_hi:[1,0,1]
	ds_read_b64 v[216:217], v3 offset:43008
	v_pk_fma_f32 v[164:165], v[86:87], v[10:11], v[164:165] op_sel:[0,1,0] op_sel_hi:[1,1,1]
	v_pk_fma_f32 v[160:161], v[86:87], v[214:215], v[160:161] op_sel:[0,1,0] op_sel_hi:[1,1,1]
	ds_read_b128 v[184:187], v2 offset:2048
	v_pk_mul_f32 v[218:219], v[26:27], v[40:41] op_sel_hi:[1,0]
	v_pk_mul_f32 v[220:221], v[26:27], v[40:41] op_sel:[0,1] op_sel_hi:[1,1]
	ds_read_b128 v[188:191], v2 offset:2064
	v_pk_mul_f32 v[222:223], v[26:27], v[42:43] op_sel_hi:[1,0]
	v_pk_mul_f32 v[224:225], v[26:27], v[42:43] op_sel:[0,1] op_sel_hi:[1,1]
	ds_read_b128 v[192:195], v2 offset:10240
	v_pk_mul_f32 v[226:227], v[26:27], v[44:45] op_sel_hi:[1,0]
	v_pk_mul_f32 v[228:229], v[26:27], v[44:45] op_sel:[0,1] op_sel_hi:[1,1]
	ds_read_b128 v[196:199], v2 offset:10256
	v_pk_mul_f32 v[230:231], v[26:27], v[46:47] op_sel_hi:[1,0]
	v_pk_mul_f32 v[234:235], v[26:27], v[46:47] op_sel:[0,1] op_sel_hi:[1,1]
	v_pk_fma_f32 v[218:219], v[72:73], v[12:13], v[218:219] op_sel_hi:[1,0,1]
	v_pk_fma_f32 v[220:221], v[74:75], v[12:13], v[220:221] op_sel:[0,1,0] op_sel_hi:[1,1,1]
	v_pk_fma_f32 v[222:223], v[76:77], v[14:15], v[222:223] op_sel_hi:[1,0,1]
	v_pk_fma_f32 v[224:225], v[78:79], v[14:15], v[224:225] op_sel:[0,1,0] op_sel_hi:[1,1,1]
	v_add_f32_dpp v164, v164, v164 quad_perm:[1,0,3,2] row_mask:0xf bank_mask:0xf bound_ctrl:1
	v_add_f32_dpp v165, v165, v165 quad_perm:[1,0,3,2] row_mask:0xf bank_mask:0xf bound_ctrl:1
	v_add_f32_dpp v160, v160, v160 quad_perm:[1,0,3,2] row_mask:0xf bank_mask:0xf bound_ctrl:1
	v_add_f32_dpp v161, v161, v161 quad_perm:[1,0,3,2] row_mask:0xf bank_mask:0xf bound_ctrl:1
	v_pk_fma_f32 v[226:227], v[80:81], v[28:29], v[226:227] op_sel_hi:[1,0,1]
	v_pk_fma_f32 v[228:229], v[82:83], v[28:29], v[228:229] op_sel:[0,1,0] op_sel_hi:[1,1,1]
	v_pk_fma_f32 v[230:231], v[84:85], v[30:31], v[230:231] op_sel_hi:[1,0,1]
	v_pk_fma_f32 v[234:235], v[86:87], v[30:31], v[234:235] op_sel:[0,1,0] op_sel_hi:[1,1,1]
	v_add_f32_dpp v164, v164, v164 quad_perm:[2,3,0,1] row_mask:0xf bank_mask:0xf bound_ctrl:1
	v_add_f32_dpp v165, v165, v165 quad_perm:[2,3,0,1] row_mask:0xf bank_mask:0xf bound_ctrl:1
	v_add_f32_dpp v160, v160, v160 quad_perm:[2,3,0,1] row_mask:0xf bank_mask:0xf bound_ctrl:1
	v_add_f32_dpp v161, v161, v161 quad_perm:[2,3,0,1] row_mask:0xf bank_mask:0xf bound_ctrl:1
	v_add_f32_dpp v164, v164, v164 row_half_mirror row_mask:0xf bank_mask:0xf bound_ctrl:1
	v_add_f32_dpp v165, v165, v165 row_half_mirror row_mask:0xf bank_mask:0xf bound_ctrl:1
	v_add_f32_dpp v160, v160, v160 row_half_mirror row_mask:0xf bank_mask:0xf bound_ctrl:1
	v_add_f32_dpp v161, v161, v161 row_half_mirror row_mask:0xf bank_mask:0xf bound_ctrl:1
	v_pk_fma_f32 v[72:73], v[32:33], v[164:165], v[218:219] op_sel_hi:[0,1,1]
	v_pk_fma_f32 v[74:75], v[32:33], v[164:165], v[220:221] op_sel:[1,0,0] op_sel_hi:[1,1,1]
	v_pk_fma_f32 v[76:77], v[34:35], v[164:165], v[222:223] op_sel_hi:[0,1,1]
	v_pk_fma_f32 v[78:79], v[34:35], v[164:165], v[224:225] op_sel:[1,0,0] op_sel_hi:[1,1,1]
	v_pk_fma_f32 v[80:81], v[36:37], v[164:165], v[226:227] op_sel_hi:[0,1,1]
	v_pk_fma_f32 v[82:83], v[36:37], v[164:165], v[228:229] op_sel:[1,0,0] op_sel_hi:[1,1,1]
	v_pk_fma_f32 v[84:85], v[38:39], v[164:165], v[230:231] op_sel_hi:[0,1,1]
	v_pk_fma_f32 v[86:87], v[38:39], v[164:165], v[234:235] op_sel:[1,0,0] op_sel_hi:[1,1,1]
	ds_write_b64 v1, v[160:161] offset:55552
	s_waitcnt lgkmcnt(1)
	v_pk_mul_f32 v[164:165], v[72:73], v[176:177] op_sel_hi:[1,0]
	v_pk_mul_f32 v[160:161], v[72:73], v[48:49] op_sel_hi:[1,0]
	ds_read_b128 v[208:211], v2 offset:18432
	v_pk_fma_f32 v[164:165], v[74:75], v[176:177], v[164:165] op_sel:[0,1,0] op_sel_hi:[1,1,1]
	v_pk_fma_f32 v[160:161], v[74:75], v[48:49], v[160:161] op_sel:[0,1,0] op_sel_hi:[1,1,1]
	ds_read_b128 v[212:215], v2 offset:18448
	v_pk_fma_f32 v[164:165], v[76:77], v[178:179], v[164:165] op_sel_hi:[1,0,1]
	v_pk_fma_f32 v[160:161], v[76:77], v[50:51], v[160:161] op_sel_hi:[1,0,1]
	ds_read_b128 v[4:7], v2 offset:6400
	v_pk_fma_f32 v[164:165], v[78:79], v[178:179], v[164:165] op_sel:[0,1,0] op_sel_hi:[1,1,1]
	v_pk_fma_f32 v[160:161], v[78:79], v[50:51], v[160:161] op_sel:[0,1,0] op_sel_hi:[1,1,1]
	ds_read_b128 v[8:11], v2 offset:6416
	v_pk_fma_f32 v[164:165], v[80:81], v[180:181], v[164:165] op_sel_hi:[1,0,1]
	v_pk_fma_f32 v[160:161], v[80:81], v[52:53], v[160:161] op_sel_hi:[1,0,1]
	ds_read_b128 v[40:43], v2 offset:14592
	v_pk_fma_f32 v[164:165], v[82:83], v[180:181], v[164:165] op_sel:[0,1,0] op_sel_hi:[1,1,1]
	v_pk_fma_f32 v[160:161], v[82:83], v[52:53], v[160:161] op_sel:[0,1,0] op_sel_hi:[1,1,1]
	ds_read_b128 v[44:47], v2 offset:14608
	v_pk_fma_f32 v[164:165], v[84:85], v[182:183], v[164:165] op_sel_hi:[1,0,1]
	v_pk_fma_f32 v[160:161], v[84:85], v[54:55], v[160:161] op_sel_hi:[1,0,1]
	ds_read_b64 v[26:27], v3 offset:43264
	v_pk_fma_f32 v[164:165], v[86:87], v[182:183], v[164:165] op_sel:[0,1,0] op_sel_hi:[1,1,1]
	v_pk_fma_f32 v[160:161], v[86:87], v[54:55], v[160:161] op_sel:[0,1,0] op_sel_hi:[1,1,1]
	ds_read_b128 v[12:15], v2 offset:2304
	v_pk_mul_f32 v[218:219], v[216:217], v[200:201] op_sel_hi:[1,0]
	v_pk_mul_f32 v[220:221], v[216:217], v[200:201] op_sel:[0,1] op_sel_hi:[1,1]
	ds_read_b128 v[28:31], v2 offset:2320
	v_pk_mul_f32 v[222:223], v[216:217], v[202:203] op_sel_hi:[1,0]
	v_pk_mul_f32 v[224:225], v[216:217], v[202:203] op_sel:[0,1] op_sel_hi:[1,1]
	ds_read_b128 v[32:35], v2 offset:10496
	v_pk_mul_f32 v[226:227], v[216:217], v[204:205] op_sel_hi:[1,0]
	v_pk_mul_f32 v[228:229], v[216:217], v[204:205] op_sel:[0,1] op_sel_hi:[1,1]
	ds_read_b128 v[36:39], v2 offset:10512
	v_pk_mul_f32 v[230:231], v[216:217], v[206:207] op_sel_hi:[1,0]
	v_pk_mul_f32 v[234:235], v[216:217], v[206:207] op_sel:[0,1] op_sel_hi:[1,1]
	v_pk_fma_f32 v[218:219], v[72:73], v[184:185], v[218:219] op_sel_hi:[1,0,1]
	v_pk_fma_f32 v[220:221], v[74:75], v[184:185], v[220:221] op_sel:[0,1,0] op_sel_hi:[1,1,1]
	v_pk_fma_f32 v[222:223], v[76:77], v[186:187], v[222:223] op_sel_hi:[1,0,1]
	v_pk_fma_f32 v[224:225], v[78:79], v[186:187], v[224:225] op_sel:[0,1,0] op_sel_hi:[1,1,1]
	v_add_f32_dpp v164, v164, v164 quad_perm:[1,0,3,2] row_mask:0xf bank_mask:0xf bound_ctrl:1
	v_add_f32_dpp v165, v165, v165 quad_perm:[1,0,3,2] row_mask:0xf bank_mask:0xf bound_ctrl:1
	v_add_f32_dpp v160, v160, v160 quad_perm:[1,0,3,2] row_mask:0xf bank_mask:0xf bound_ctrl:1
	v_add_f32_dpp v161, v161, v161 quad_perm:[1,0,3,2] row_mask:0xf bank_mask:0xf bound_ctrl:1
	v_pk_fma_f32 v[226:227], v[80:81], v[188:189], v[226:227] op_sel_hi:[1,0,1]
	v_pk_fma_f32 v[228:229], v[82:83], v[188:189], v[228:229] op_sel:[0,1,0] op_sel_hi:[1,1,1]
	v_pk_fma_f32 v[230:231], v[84:85], v[190:191], v[230:231] op_sel_hi:[1,0,1]
	v_pk_fma_f32 v[234:235], v[86:87], v[190:191], v[234:235] op_sel:[0,1,0] op_sel_hi:[1,1,1]
	v_add_f32_dpp v164, v164, v164 quad_perm:[2,3,0,1] row_mask:0xf bank_mask:0xf bound_ctrl:1
	v_add_f32_dpp v165, v165, v165 quad_perm:[2,3,0,1] row_mask:0xf bank_mask:0xf bound_ctrl:1
	v_add_f32_dpp v160, v160, v160 quad_perm:[2,3,0,1] row_mask:0xf bank_mask:0xf bound_ctrl:1
	v_add_f32_dpp v161, v161, v161 quad_perm:[2,3,0,1] row_mask:0xf bank_mask:0xf bound_ctrl:1
	v_add_f32_dpp v164, v164, v164 row_half_mirror row_mask:0xf bank_mask:0xf bound_ctrl:1
	v_add_f32_dpp v165, v165, v165 row_half_mirror row_mask:0xf bank_mask:0xf bound_ctrl:1
	v_add_f32_dpp v160, v160, v160 row_half_mirror row_mask:0xf bank_mask:0xf bound_ctrl:1
	v_add_f32_dpp v161, v161, v161 row_half_mirror row_mask:0xf bank_mask:0xf bound_ctrl:1
	v_pk_fma_f32 v[72:73], v[192:193], v[164:165], v[218:219] op_sel_hi:[0,1,1]
	v_pk_fma_f32 v[74:75], v[192:193], v[164:165], v[220:221] op_sel:[1,0,0] op_sel_hi:[1,1,1]
	v_pk_fma_f32 v[76:77], v[194:195], v[164:165], v[222:223] op_sel_hi:[0,1,1]
	v_pk_fma_f32 v[78:79], v[194:195], v[164:165], v[224:225] op_sel:[1,0,0] op_sel_hi:[1,1,1]
	v_pk_fma_f32 v[80:81], v[196:197], v[164:165], v[226:227] op_sel_hi:[0,1,1]
	v_pk_fma_f32 v[82:83], v[196:197], v[164:165], v[228:229] op_sel:[1,0,0] op_sel_hi:[1,1,1]
	v_pk_fma_f32 v[84:85], v[198:199], v[164:165], v[230:231] op_sel_hi:[0,1,1]
	v_pk_fma_f32 v[86:87], v[198:199], v[164:165], v[234:235] op_sel:[1,0,0] op_sel_hi:[1,1,1]
	ds_write_b64 v1, v[160:161] offset:55808
	s_waitcnt lgkmcnt(1)
	v_pk_mul_f32 v[164:165], v[72:73], v[4:5] op_sel_hi:[1,0]
	v_pk_mul_f32 v[160:161], v[72:73], v[208:209] op_sel_hi:[1,0]
	ds_read_b128 v[48:51], v2 offset:18688
	v_pk_fma_f32 v[164:165], v[74:75], v[4:5], v[164:165] op_sel:[0,1,0] op_sel_hi:[1,1,1]
	v_pk_fma_f32 v[160:161], v[74:75], v[208:209], v[160:161] op_sel:[0,1,0] op_sel_hi:[1,1,1]
	ds_read_b128 v[52:55], v2 offset:18704
	v_pk_fma_f32 v[164:165], v[76:77], v[6:7], v[164:165] op_sel_hi:[1,0,1]
	v_pk_fma_f32 v[160:161], v[76:77], v[210:211], v[160:161] op_sel_hi:[1,0,1]
	ds_read_b128 v[176:179], v2 offset:6656
	v_pk_fma_f32 v[164:165], v[78:79], v[6:7], v[164:165] op_sel:[0,1,0] op_sel_hi:[1,1,1]
	v_pk_fma_f32 v[160:161], v[78:79], v[210:211], v[160:161] op_sel:[0,1,0] op_sel_hi:[1,1,1]
	ds_read_b128 v[180:183], v2 offset:6672
	v_pk_fma_f32 v[164:165], v[80:81], v[8:9], v[164:165] op_sel_hi:[1,0,1]
	v_pk_fma_f32 v[160:161], v[80:81], v[212:213], v[160:161] op_sel_hi:[1,0,1]
	ds_read_b128 v[200:203], v2 offset:14848
	v_pk_fma_f32 v[164:165], v[82:83], v[8:9], v[164:165] op_sel:[0,1,0] op_sel_hi:[1,1,1]
	v_pk_fma_f32 v[160:161], v[82:83], v[212:213], v[160:161] op_sel:[0,1,0] op_sel_hi:[1,1,1]
	ds_read_b128 v[204:207], v2 offset:14864
	v_pk_fma_f32 v[164:165], v[84:85], v[10:11], v[164:165] op_sel_hi:[1,0,1]
	v_pk_fma_f32 v[160:161], v[84:85], v[214:215], v[160:161] op_sel_hi:[1,0,1]
	ds_read_b64 v[216:217], v3 offset:43520
	v_pk_fma_f32 v[164:165], v[86:87], v[10:11], v[164:165] op_sel:[0,1,0] op_sel_hi:[1,1,1]
	v_pk_fma_f32 v[160:161], v[86:87], v[214:215], v[160:161] op_sel:[0,1,0] op_sel_hi:[1,1,1]
	ds_read_b128 v[184:187], v2 offset:2560
	v_pk_mul_f32 v[218:219], v[26:27], v[40:41] op_sel_hi:[1,0]
	v_pk_mul_f32 v[220:221], v[26:27], v[40:41] op_sel:[0,1] op_sel_hi:[1,1]
	ds_read_b128 v[188:191], v2 offset:2576
	v_pk_mul_f32 v[222:223], v[26:27], v[42:43] op_sel_hi:[1,0]
	v_pk_mul_f32 v[224:225], v[26:27], v[42:43] op_sel:[0,1] op_sel_hi:[1,1]
	ds_read_b128 v[192:195], v2 offset:10752
	v_pk_mul_f32 v[226:227], v[26:27], v[44:45] op_sel_hi:[1,0]
	v_pk_mul_f32 v[228:229], v[26:27], v[44:45] op_sel:[0,1] op_sel_hi:[1,1]
	ds_read_b128 v[196:199], v2 offset:10768
	v_pk_mul_f32 v[230:231], v[26:27], v[46:47] op_sel_hi:[1,0]
	v_pk_mul_f32 v[234:235], v[26:27], v[46:47] op_sel:[0,1] op_sel_hi:[1,1]
	v_pk_fma_f32 v[218:219], v[72:73], v[12:13], v[218:219] op_sel_hi:[1,0,1]
	v_pk_fma_f32 v[220:221], v[74:75], v[12:13], v[220:221] op_sel:[0,1,0] op_sel_hi:[1,1,1]
	v_pk_fma_f32 v[222:223], v[76:77], v[14:15], v[222:223] op_sel_hi:[1,0,1]
	v_pk_fma_f32 v[224:225], v[78:79], v[14:15], v[224:225] op_sel:[0,1,0] op_sel_hi:[1,1,1]
	v_add_f32_dpp v164, v164, v164 quad_perm:[1,0,3,2] row_mask:0xf bank_mask:0xf bound_ctrl:1
	v_add_f32_dpp v165, v165, v165 quad_perm:[1,0,3,2] row_mask:0xf bank_mask:0xf bound_ctrl:1
	v_add_f32_dpp v160, v160, v160 quad_perm:[1,0,3,2] row_mask:0xf bank_mask:0xf bound_ctrl:1
	v_add_f32_dpp v161, v161, v161 quad_perm:[1,0,3,2] row_mask:0xf bank_mask:0xf bound_ctrl:1
	v_pk_fma_f32 v[226:227], v[80:81], v[28:29], v[226:227] op_sel_hi:[1,0,1]
	v_pk_fma_f32 v[228:229], v[82:83], v[28:29], v[228:229] op_sel:[0,1,0] op_sel_hi:[1,1,1]
	v_pk_fma_f32 v[230:231], v[84:85], v[30:31], v[230:231] op_sel_hi:[1,0,1]
	v_pk_fma_f32 v[234:235], v[86:87], v[30:31], v[234:235] op_sel:[0,1,0] op_sel_hi:[1,1,1]
	v_add_f32_dpp v164, v164, v164 quad_perm:[2,3,0,1] row_mask:0xf bank_mask:0xf bound_ctrl:1
	v_add_f32_dpp v165, v165, v165 quad_perm:[2,3,0,1] row_mask:0xf bank_mask:0xf bound_ctrl:1
	v_add_f32_dpp v160, v160, v160 quad_perm:[2,3,0,1] row_mask:0xf bank_mask:0xf bound_ctrl:1
	v_add_f32_dpp v161, v161, v161 quad_perm:[2,3,0,1] row_mask:0xf bank_mask:0xf bound_ctrl:1
	v_add_f32_dpp v164, v164, v164 row_half_mirror row_mask:0xf bank_mask:0xf bound_ctrl:1
	v_add_f32_dpp v165, v165, v165 row_half_mirror row_mask:0xf bank_mask:0xf bound_ctrl:1
	v_add_f32_dpp v160, v160, v160 row_half_mirror row_mask:0xf bank_mask:0xf bound_ctrl:1
	v_add_f32_dpp v161, v161, v161 row_half_mirror row_mask:0xf bank_mask:0xf bound_ctrl:1
	v_pk_fma_f32 v[72:73], v[32:33], v[164:165], v[218:219] op_sel_hi:[0,1,1]
	v_pk_fma_f32 v[74:75], v[32:33], v[164:165], v[220:221] op_sel:[1,0,0] op_sel_hi:[1,1,1]
	v_pk_fma_f32 v[76:77], v[34:35], v[164:165], v[222:223] op_sel_hi:[0,1,1]
	v_pk_fma_f32 v[78:79], v[34:35], v[164:165], v[224:225] op_sel:[1,0,0] op_sel_hi:[1,1,1]
	v_pk_fma_f32 v[80:81], v[36:37], v[164:165], v[226:227] op_sel_hi:[0,1,1]
	v_pk_fma_f32 v[82:83], v[36:37], v[164:165], v[228:229] op_sel:[1,0,0] op_sel_hi:[1,1,1]
	v_pk_fma_f32 v[84:85], v[38:39], v[164:165], v[230:231] op_sel_hi:[0,1,1]
	v_pk_fma_f32 v[86:87], v[38:39], v[164:165], v[234:235] op_sel:[1,0,0] op_sel_hi:[1,1,1]
	ds_write_b64 v1, v[160:161] offset:56064
	s_waitcnt lgkmcnt(1)
	v_pk_mul_f32 v[164:165], v[72:73], v[176:177] op_sel_hi:[1,0]
	v_pk_mul_f32 v[160:161], v[72:73], v[48:49] op_sel_hi:[1,0]
	ds_read_b128 v[208:211], v2 offset:18944
	v_pk_fma_f32 v[164:165], v[74:75], v[176:177], v[164:165] op_sel:[0,1,0] op_sel_hi:[1,1,1]
	v_pk_fma_f32 v[160:161], v[74:75], v[48:49], v[160:161] op_sel:[0,1,0] op_sel_hi:[1,1,1]
	ds_read_b128 v[212:215], v2 offset:18960
	v_pk_fma_f32 v[164:165], v[76:77], v[178:179], v[164:165] op_sel_hi:[1,0,1]
	v_pk_fma_f32 v[160:161], v[76:77], v[50:51], v[160:161] op_sel_hi:[1,0,1]
	ds_read_b128 v[4:7], v2 offset:6912
	v_pk_fma_f32 v[164:165], v[78:79], v[178:179], v[164:165] op_sel:[0,1,0] op_sel_hi:[1,1,1]
	v_pk_fma_f32 v[160:161], v[78:79], v[50:51], v[160:161] op_sel:[0,1,0] op_sel_hi:[1,1,1]
	ds_read_b128 v[8:11], v2 offset:6928
	v_pk_fma_f32 v[164:165], v[80:81], v[180:181], v[164:165] op_sel_hi:[1,0,1]
	v_pk_fma_f32 v[160:161], v[80:81], v[52:53], v[160:161] op_sel_hi:[1,0,1]
	ds_read_b128 v[40:43], v2 offset:15104
	v_pk_fma_f32 v[164:165], v[82:83], v[180:181], v[164:165] op_sel:[0,1,0] op_sel_hi:[1,1,1]
	v_pk_fma_f32 v[160:161], v[82:83], v[52:53], v[160:161] op_sel:[0,1,0] op_sel_hi:[1,1,1]
	ds_read_b128 v[44:47], v2 offset:15120
	v_pk_fma_f32 v[164:165], v[84:85], v[182:183], v[164:165] op_sel_hi:[1,0,1]
	v_pk_fma_f32 v[160:161], v[84:85], v[54:55], v[160:161] op_sel_hi:[1,0,1]
	ds_read_b64 v[26:27], v3 offset:43776
	v_pk_fma_f32 v[164:165], v[86:87], v[182:183], v[164:165] op_sel:[0,1,0] op_sel_hi:[1,1,1]
	v_pk_fma_f32 v[160:161], v[86:87], v[54:55], v[160:161] op_sel:[0,1,0] op_sel_hi:[1,1,1]
	ds_read_b128 v[12:15], v2 offset:2816
	v_pk_mul_f32 v[218:219], v[216:217], v[200:201] op_sel_hi:[1,0]
	v_pk_mul_f32 v[220:221], v[216:217], v[200:201] op_sel:[0,1] op_sel_hi:[1,1]
	ds_read_b128 v[28:31], v2 offset:2832
	v_pk_mul_f32 v[222:223], v[216:217], v[202:203] op_sel_hi:[1,0]
	v_pk_mul_f32 v[224:225], v[216:217], v[202:203] op_sel:[0,1] op_sel_hi:[1,1]
	ds_read_b128 v[32:35], v2 offset:11008
	v_pk_mul_f32 v[226:227], v[216:217], v[204:205] op_sel_hi:[1,0]
	v_pk_mul_f32 v[228:229], v[216:217], v[204:205] op_sel:[0,1] op_sel_hi:[1,1]
	ds_read_b128 v[36:39], v2 offset:11024
	v_pk_mul_f32 v[230:231], v[216:217], v[206:207] op_sel_hi:[1,0]
	v_pk_mul_f32 v[234:235], v[216:217], v[206:207] op_sel:[0,1] op_sel_hi:[1,1]
	v_pk_fma_f32 v[218:219], v[72:73], v[184:185], v[218:219] op_sel_hi:[1,0,1]
	v_pk_fma_f32 v[220:221], v[74:75], v[184:185], v[220:221] op_sel:[0,1,0] op_sel_hi:[1,1,1]
	v_pk_fma_f32 v[222:223], v[76:77], v[186:187], v[222:223] op_sel_hi:[1,0,1]
	v_pk_fma_f32 v[224:225], v[78:79], v[186:187], v[224:225] op_sel:[0,1,0] op_sel_hi:[1,1,1]
	v_add_f32_dpp v164, v164, v164 quad_perm:[1,0,3,2] row_mask:0xf bank_mask:0xf bound_ctrl:1
	v_add_f32_dpp v165, v165, v165 quad_perm:[1,0,3,2] row_mask:0xf bank_mask:0xf bound_ctrl:1
	v_add_f32_dpp v160, v160, v160 quad_perm:[1,0,3,2] row_mask:0xf bank_mask:0xf bound_ctrl:1
	v_add_f32_dpp v161, v161, v161 quad_perm:[1,0,3,2] row_mask:0xf bank_mask:0xf bound_ctrl:1
	v_pk_fma_f32 v[226:227], v[80:81], v[188:189], v[226:227] op_sel_hi:[1,0,1]
	v_pk_fma_f32 v[228:229], v[82:83], v[188:189], v[228:229] op_sel:[0,1,0] op_sel_hi:[1,1,1]
	v_pk_fma_f32 v[230:231], v[84:85], v[190:191], v[230:231] op_sel_hi:[1,0,1]
	v_pk_fma_f32 v[234:235], v[86:87], v[190:191], v[234:235] op_sel:[0,1,0] op_sel_hi:[1,1,1]
	v_add_f32_dpp v164, v164, v164 quad_perm:[2,3,0,1] row_mask:0xf bank_mask:0xf bound_ctrl:1
	v_add_f32_dpp v165, v165, v165 quad_perm:[2,3,0,1] row_mask:0xf bank_mask:0xf bound_ctrl:1
	v_add_f32_dpp v160, v160, v160 quad_perm:[2,3,0,1] row_mask:0xf bank_mask:0xf bound_ctrl:1
	v_add_f32_dpp v161, v161, v161 quad_perm:[2,3,0,1] row_mask:0xf bank_mask:0xf bound_ctrl:1
	v_add_f32_dpp v164, v164, v164 row_half_mirror row_mask:0xf bank_mask:0xf bound_ctrl:1
	v_add_f32_dpp v165, v165, v165 row_half_mirror row_mask:0xf bank_mask:0xf bound_ctrl:1
	v_add_f32_dpp v160, v160, v160 row_half_mirror row_mask:0xf bank_mask:0xf bound_ctrl:1
	v_add_f32_dpp v161, v161, v161 row_half_mirror row_mask:0xf bank_mask:0xf bound_ctrl:1
	v_pk_fma_f32 v[72:73], v[192:193], v[164:165], v[218:219] op_sel_hi:[0,1,1]
	v_pk_fma_f32 v[74:75], v[192:193], v[164:165], v[220:221] op_sel:[1,0,0] op_sel_hi:[1,1,1]
	v_pk_fma_f32 v[76:77], v[194:195], v[164:165], v[222:223] op_sel_hi:[0,1,1]
	v_pk_fma_f32 v[78:79], v[194:195], v[164:165], v[224:225] op_sel:[1,0,0] op_sel_hi:[1,1,1]
	v_pk_fma_f32 v[80:81], v[196:197], v[164:165], v[226:227] op_sel_hi:[0,1,1]
	v_pk_fma_f32 v[82:83], v[196:197], v[164:165], v[228:229] op_sel:[1,0,0] op_sel_hi:[1,1,1]
	v_pk_fma_f32 v[84:85], v[198:199], v[164:165], v[230:231] op_sel_hi:[0,1,1]
	v_pk_fma_f32 v[86:87], v[198:199], v[164:165], v[234:235] op_sel:[1,0,0] op_sel_hi:[1,1,1]
	ds_write_b64 v1, v[160:161] offset:56320
	s_waitcnt lgkmcnt(1)
	v_pk_mul_f32 v[164:165], v[72:73], v[4:5] op_sel_hi:[1,0]
	v_pk_mul_f32 v[160:161], v[72:73], v[208:209] op_sel_hi:[1,0]
	ds_read_b128 v[48:51], v2 offset:19200
	v_pk_fma_f32 v[164:165], v[74:75], v[4:5], v[164:165] op_sel:[0,1,0] op_sel_hi:[1,1,1]
	v_pk_fma_f32 v[160:161], v[74:75], v[208:209], v[160:161] op_sel:[0,1,0] op_sel_hi:[1,1,1]
	ds_read_b128 v[52:55], v2 offset:19216
	v_pk_fma_f32 v[164:165], v[76:77], v[6:7], v[164:165] op_sel_hi:[1,0,1]
	v_pk_fma_f32 v[160:161], v[76:77], v[210:211], v[160:161] op_sel_hi:[1,0,1]
	ds_read_b128 v[176:179], v2 offset:7168
	v_pk_fma_f32 v[164:165], v[78:79], v[6:7], v[164:165] op_sel:[0,1,0] op_sel_hi:[1,1,1]
	v_pk_fma_f32 v[160:161], v[78:79], v[210:211], v[160:161] op_sel:[0,1,0] op_sel_hi:[1,1,1]
	ds_read_b128 v[180:183], v2 offset:7184
	v_pk_fma_f32 v[164:165], v[80:81], v[8:9], v[164:165] op_sel_hi:[1,0,1]
	v_pk_fma_f32 v[160:161], v[80:81], v[212:213], v[160:161] op_sel_hi:[1,0,1]
	ds_read_b128 v[200:203], v2 offset:15360
	v_pk_fma_f32 v[164:165], v[82:83], v[8:9], v[164:165] op_sel:[0,1,0] op_sel_hi:[1,1,1]
	v_pk_fma_f32 v[160:161], v[82:83], v[212:213], v[160:161] op_sel:[0,1,0] op_sel_hi:[1,1,1]
	ds_read_b128 v[204:207], v2 offset:15376
	v_pk_fma_f32 v[164:165], v[84:85], v[10:11], v[164:165] op_sel_hi:[1,0,1]
	v_pk_fma_f32 v[160:161], v[84:85], v[214:215], v[160:161] op_sel_hi:[1,0,1]
	ds_read_b64 v[216:217], v3 offset:44032
	v_pk_fma_f32 v[164:165], v[86:87], v[10:11], v[164:165] op_sel:[0,1,0] op_sel_hi:[1,1,1]
	v_pk_fma_f32 v[160:161], v[86:87], v[214:215], v[160:161] op_sel:[0,1,0] op_sel_hi:[1,1,1]
	ds_read_b128 v[184:187], v2 offset:3072
	v_pk_mul_f32 v[218:219], v[26:27], v[40:41] op_sel_hi:[1,0]
	v_pk_mul_f32 v[220:221], v[26:27], v[40:41] op_sel:[0,1] op_sel_hi:[1,1]
	ds_read_b128 v[188:191], v2 offset:3088
	v_pk_mul_f32 v[222:223], v[26:27], v[42:43] op_sel_hi:[1,0]
	v_pk_mul_f32 v[224:225], v[26:27], v[42:43] op_sel:[0,1] op_sel_hi:[1,1]
	ds_read_b128 v[192:195], v2 offset:11264
	v_pk_mul_f32 v[226:227], v[26:27], v[44:45] op_sel_hi:[1,0]
	v_pk_mul_f32 v[228:229], v[26:27], v[44:45] op_sel:[0,1] op_sel_hi:[1,1]
	ds_read_b128 v[196:199], v2 offset:11280
	v_pk_mul_f32 v[230:231], v[26:27], v[46:47] op_sel_hi:[1,0]
	v_pk_mul_f32 v[234:235], v[26:27], v[46:47] op_sel:[0,1] op_sel_hi:[1,1]
	v_pk_fma_f32 v[218:219], v[72:73], v[12:13], v[218:219] op_sel_hi:[1,0,1]
	v_pk_fma_f32 v[220:221], v[74:75], v[12:13], v[220:221] op_sel:[0,1,0] op_sel_hi:[1,1,1]
	v_pk_fma_f32 v[222:223], v[76:77], v[14:15], v[222:223] op_sel_hi:[1,0,1]
	v_pk_fma_f32 v[224:225], v[78:79], v[14:15], v[224:225] op_sel:[0,1,0] op_sel_hi:[1,1,1]
	v_add_f32_dpp v164, v164, v164 quad_perm:[1,0,3,2] row_mask:0xf bank_mask:0xf bound_ctrl:1
	v_add_f32_dpp v165, v165, v165 quad_perm:[1,0,3,2] row_mask:0xf bank_mask:0xf bound_ctrl:1
	v_add_f32_dpp v160, v160, v160 quad_perm:[1,0,3,2] row_mask:0xf bank_mask:0xf bound_ctrl:1
	v_add_f32_dpp v161, v161, v161 quad_perm:[1,0,3,2] row_mask:0xf bank_mask:0xf bound_ctrl:1
	v_pk_fma_f32 v[226:227], v[80:81], v[28:29], v[226:227] op_sel_hi:[1,0,1]
	v_pk_fma_f32 v[228:229], v[82:83], v[28:29], v[228:229] op_sel:[0,1,0] op_sel_hi:[1,1,1]
	v_pk_fma_f32 v[230:231], v[84:85], v[30:31], v[230:231] op_sel_hi:[1,0,1]
	v_pk_fma_f32 v[234:235], v[86:87], v[30:31], v[234:235] op_sel:[0,1,0] op_sel_hi:[1,1,1]
	v_add_f32_dpp v164, v164, v164 quad_perm:[2,3,0,1] row_mask:0xf bank_mask:0xf bound_ctrl:1
	v_add_f32_dpp v165, v165, v165 quad_perm:[2,3,0,1] row_mask:0xf bank_mask:0xf bound_ctrl:1
	v_add_f32_dpp v160, v160, v160 quad_perm:[2,3,0,1] row_mask:0xf bank_mask:0xf bound_ctrl:1
	v_add_f32_dpp v161, v161, v161 quad_perm:[2,3,0,1] row_mask:0xf bank_mask:0xf bound_ctrl:1
	v_add_f32_dpp v164, v164, v164 row_half_mirror row_mask:0xf bank_mask:0xf bound_ctrl:1
	v_add_f32_dpp v165, v165, v165 row_half_mirror row_mask:0xf bank_mask:0xf bound_ctrl:1
	v_add_f32_dpp v160, v160, v160 row_half_mirror row_mask:0xf bank_mask:0xf bound_ctrl:1
	v_add_f32_dpp v161, v161, v161 row_half_mirror row_mask:0xf bank_mask:0xf bound_ctrl:1
	v_pk_fma_f32 v[72:73], v[32:33], v[164:165], v[218:219] op_sel_hi:[0,1,1]
	v_pk_fma_f32 v[74:75], v[32:33], v[164:165], v[220:221] op_sel:[1,0,0] op_sel_hi:[1,1,1]
	v_pk_fma_f32 v[76:77], v[34:35], v[164:165], v[222:223] op_sel_hi:[0,1,1]
	v_pk_fma_f32 v[78:79], v[34:35], v[164:165], v[224:225] op_sel:[1,0,0] op_sel_hi:[1,1,1]
	v_pk_fma_f32 v[80:81], v[36:37], v[164:165], v[226:227] op_sel_hi:[0,1,1]
	v_pk_fma_f32 v[82:83], v[36:37], v[164:165], v[228:229] op_sel:[1,0,0] op_sel_hi:[1,1,1]
	v_pk_fma_f32 v[84:85], v[38:39], v[164:165], v[230:231] op_sel_hi:[0,1,1]
	v_pk_fma_f32 v[86:87], v[38:39], v[164:165], v[234:235] op_sel:[1,0,0] op_sel_hi:[1,1,1]
	ds_write_b64 v1, v[160:161] offset:56576
	s_waitcnt lgkmcnt(1)
	v_pk_mul_f32 v[164:165], v[72:73], v[176:177] op_sel_hi:[1,0]
	v_pk_mul_f32 v[160:161], v[72:73], v[48:49] op_sel_hi:[1,0]
	ds_read_b128 v[208:211], v2 offset:19456
	v_pk_fma_f32 v[164:165], v[74:75], v[176:177], v[164:165] op_sel:[0,1,0] op_sel_hi:[1,1,1]
	v_pk_fma_f32 v[160:161], v[74:75], v[48:49], v[160:161] op_sel:[0,1,0] op_sel_hi:[1,1,1]
	ds_read_b128 v[212:215], v2 offset:19472
	v_pk_fma_f32 v[164:165], v[76:77], v[178:179], v[164:165] op_sel_hi:[1,0,1]
	v_pk_fma_f32 v[160:161], v[76:77], v[50:51], v[160:161] op_sel_hi:[1,0,1]
	ds_read_b128 v[4:7], v2 offset:7424
	v_pk_fma_f32 v[164:165], v[78:79], v[178:179], v[164:165] op_sel:[0,1,0] op_sel_hi:[1,1,1]
	v_pk_fma_f32 v[160:161], v[78:79], v[50:51], v[160:161] op_sel:[0,1,0] op_sel_hi:[1,1,1]
	ds_read_b128 v[8:11], v2 offset:7440
	v_pk_fma_f32 v[164:165], v[80:81], v[180:181], v[164:165] op_sel_hi:[1,0,1]
	v_pk_fma_f32 v[160:161], v[80:81], v[52:53], v[160:161] op_sel_hi:[1,0,1]
	ds_read_b128 v[40:43], v2 offset:15616
	v_pk_fma_f32 v[164:165], v[82:83], v[180:181], v[164:165] op_sel:[0,1,0] op_sel_hi:[1,1,1]
	v_pk_fma_f32 v[160:161], v[82:83], v[52:53], v[160:161] op_sel:[0,1,0] op_sel_hi:[1,1,1]
	ds_read_b128 v[44:47], v2 offset:15632
	v_pk_fma_f32 v[164:165], v[84:85], v[182:183], v[164:165] op_sel_hi:[1,0,1]
	v_pk_fma_f32 v[160:161], v[84:85], v[54:55], v[160:161] op_sel_hi:[1,0,1]
	ds_read_b64 v[26:27], v3 offset:44288
	v_pk_fma_f32 v[164:165], v[86:87], v[182:183], v[164:165] op_sel:[0,1,0] op_sel_hi:[1,1,1]
	v_pk_fma_f32 v[160:161], v[86:87], v[54:55], v[160:161] op_sel:[0,1,0] op_sel_hi:[1,1,1]
	ds_read_b128 v[12:15], v2 offset:3328
	v_pk_mul_f32 v[218:219], v[216:217], v[200:201] op_sel_hi:[1,0]
	v_pk_mul_f32 v[220:221], v[216:217], v[200:201] op_sel:[0,1] op_sel_hi:[1,1]
	ds_read_b128 v[28:31], v2 offset:3344
	v_pk_mul_f32 v[222:223], v[216:217], v[202:203] op_sel_hi:[1,0]
	v_pk_mul_f32 v[224:225], v[216:217], v[202:203] op_sel:[0,1] op_sel_hi:[1,1]
	ds_read_b128 v[32:35], v2 offset:11520
	v_pk_mul_f32 v[226:227], v[216:217], v[204:205] op_sel_hi:[1,0]
	v_pk_mul_f32 v[228:229], v[216:217], v[204:205] op_sel:[0,1] op_sel_hi:[1,1]
	ds_read_b128 v[36:39], v2 offset:11536
	v_pk_mul_f32 v[230:231], v[216:217], v[206:207] op_sel_hi:[1,0]
	v_pk_mul_f32 v[234:235], v[216:217], v[206:207] op_sel:[0,1] op_sel_hi:[1,1]
	v_pk_fma_f32 v[218:219], v[72:73], v[184:185], v[218:219] op_sel_hi:[1,0,1]
	v_pk_fma_f32 v[220:221], v[74:75], v[184:185], v[220:221] op_sel:[0,1,0] op_sel_hi:[1,1,1]
	v_pk_fma_f32 v[222:223], v[76:77], v[186:187], v[222:223] op_sel_hi:[1,0,1]
	v_pk_fma_f32 v[224:225], v[78:79], v[186:187], v[224:225] op_sel:[0,1,0] op_sel_hi:[1,1,1]
	v_add_f32_dpp v164, v164, v164 quad_perm:[1,0,3,2] row_mask:0xf bank_mask:0xf bound_ctrl:1
	v_add_f32_dpp v165, v165, v165 quad_perm:[1,0,3,2] row_mask:0xf bank_mask:0xf bound_ctrl:1
	v_add_f32_dpp v160, v160, v160 quad_perm:[1,0,3,2] row_mask:0xf bank_mask:0xf bound_ctrl:1
	v_add_f32_dpp v161, v161, v161 quad_perm:[1,0,3,2] row_mask:0xf bank_mask:0xf bound_ctrl:1
	v_pk_fma_f32 v[226:227], v[80:81], v[188:189], v[226:227] op_sel_hi:[1,0,1]
	v_pk_fma_f32 v[228:229], v[82:83], v[188:189], v[228:229] op_sel:[0,1,0] op_sel_hi:[1,1,1]
	v_pk_fma_f32 v[230:231], v[84:85], v[190:191], v[230:231] op_sel_hi:[1,0,1]
	v_pk_fma_f32 v[234:235], v[86:87], v[190:191], v[234:235] op_sel:[0,1,0] op_sel_hi:[1,1,1]
	v_add_f32_dpp v164, v164, v164 quad_perm:[2,3,0,1] row_mask:0xf bank_mask:0xf bound_ctrl:1
	v_add_f32_dpp v165, v165, v165 quad_perm:[2,3,0,1] row_mask:0xf bank_mask:0xf bound_ctrl:1
	v_add_f32_dpp v160, v160, v160 quad_perm:[2,3,0,1] row_mask:0xf bank_mask:0xf bound_ctrl:1
	v_add_f32_dpp v161, v161, v161 quad_perm:[2,3,0,1] row_mask:0xf bank_mask:0xf bound_ctrl:1
	v_add_f32_dpp v164, v164, v164 row_half_mirror row_mask:0xf bank_mask:0xf bound_ctrl:1
	v_add_f32_dpp v165, v165, v165 row_half_mirror row_mask:0xf bank_mask:0xf bound_ctrl:1
	v_add_f32_dpp v160, v160, v160 row_half_mirror row_mask:0xf bank_mask:0xf bound_ctrl:1
	v_add_f32_dpp v161, v161, v161 row_half_mirror row_mask:0xf bank_mask:0xf bound_ctrl:1
	v_pk_fma_f32 v[72:73], v[192:193], v[164:165], v[218:219] op_sel_hi:[0,1,1]
	v_pk_fma_f32 v[74:75], v[192:193], v[164:165], v[220:221] op_sel:[1,0,0] op_sel_hi:[1,1,1]
	v_pk_fma_f32 v[76:77], v[194:195], v[164:165], v[222:223] op_sel_hi:[0,1,1]
	v_pk_fma_f32 v[78:79], v[194:195], v[164:165], v[224:225] op_sel:[1,0,0] op_sel_hi:[1,1,1]
	v_pk_fma_f32 v[80:81], v[196:197], v[164:165], v[226:227] op_sel_hi:[0,1,1]
	v_pk_fma_f32 v[82:83], v[196:197], v[164:165], v[228:229] op_sel:[1,0,0] op_sel_hi:[1,1,1]
	v_pk_fma_f32 v[84:85], v[198:199], v[164:165], v[230:231] op_sel_hi:[0,1,1]
	v_pk_fma_f32 v[86:87], v[198:199], v[164:165], v[234:235] op_sel:[1,0,0] op_sel_hi:[1,1,1]
	ds_write_b64 v1, v[160:161] offset:56832
	s_waitcnt lgkmcnt(1)
	v_pk_mul_f32 v[164:165], v[72:73], v[4:5] op_sel_hi:[1,0]
	v_pk_mul_f32 v[160:161], v[72:73], v[208:209] op_sel_hi:[1,0]
	ds_read_b128 v[48:51], v2 offset:19712
	v_pk_fma_f32 v[164:165], v[74:75], v[4:5], v[164:165] op_sel:[0,1,0] op_sel_hi:[1,1,1]
	v_pk_fma_f32 v[160:161], v[74:75], v[208:209], v[160:161] op_sel:[0,1,0] op_sel_hi:[1,1,1]
	ds_read_b128 v[52:55], v2 offset:19728
	v_pk_fma_f32 v[164:165], v[76:77], v[6:7], v[164:165] op_sel_hi:[1,0,1]
	v_pk_fma_f32 v[160:161], v[76:77], v[210:211], v[160:161] op_sel_hi:[1,0,1]
	ds_read_b128 v[176:179], v2 offset:7680
	v_pk_fma_f32 v[164:165], v[78:79], v[6:7], v[164:165] op_sel:[0,1,0] op_sel_hi:[1,1,1]
	v_pk_fma_f32 v[160:161], v[78:79], v[210:211], v[160:161] op_sel:[0,1,0] op_sel_hi:[1,1,1]
	ds_read_b128 v[180:183], v2 offset:7696
	v_pk_fma_f32 v[164:165], v[80:81], v[8:9], v[164:165] op_sel_hi:[1,0,1]
	v_pk_fma_f32 v[160:161], v[80:81], v[212:213], v[160:161] op_sel_hi:[1,0,1]
	ds_read_b128 v[200:203], v2 offset:15872
	v_pk_fma_f32 v[164:165], v[82:83], v[8:9], v[164:165] op_sel:[0,1,0] op_sel_hi:[1,1,1]
	v_pk_fma_f32 v[160:161], v[82:83], v[212:213], v[160:161] op_sel:[0,1,0] op_sel_hi:[1,1,1]
	ds_read_b128 v[204:207], v2 offset:15888
	v_pk_fma_f32 v[164:165], v[84:85], v[10:11], v[164:165] op_sel_hi:[1,0,1]
	v_pk_fma_f32 v[160:161], v[84:85], v[214:215], v[160:161] op_sel_hi:[1,0,1]
	ds_read_b64 v[216:217], v3 offset:44544
	v_pk_fma_f32 v[164:165], v[86:87], v[10:11], v[164:165] op_sel:[0,1,0] op_sel_hi:[1,1,1]
	v_pk_fma_f32 v[160:161], v[86:87], v[214:215], v[160:161] op_sel:[0,1,0] op_sel_hi:[1,1,1]
	ds_read_b128 v[184:187], v2 offset:3584
	v_pk_mul_f32 v[218:219], v[26:27], v[40:41] op_sel_hi:[1,0]
	v_pk_mul_f32 v[220:221], v[26:27], v[40:41] op_sel:[0,1] op_sel_hi:[1,1]
	ds_read_b128 v[188:191], v2 offset:3600
	v_pk_mul_f32 v[222:223], v[26:27], v[42:43] op_sel_hi:[1,0]
	v_pk_mul_f32 v[224:225], v[26:27], v[42:43] op_sel:[0,1] op_sel_hi:[1,1]
	ds_read_b128 v[192:195], v2 offset:11776
	v_pk_mul_f32 v[226:227], v[26:27], v[44:45] op_sel_hi:[1,0]
	v_pk_mul_f32 v[228:229], v[26:27], v[44:45] op_sel:[0,1] op_sel_hi:[1,1]
	ds_read_b128 v[196:199], v2 offset:11792
	v_pk_mul_f32 v[230:231], v[26:27], v[46:47] op_sel_hi:[1,0]
	v_pk_mul_f32 v[234:235], v[26:27], v[46:47] op_sel:[0,1] op_sel_hi:[1,1]
	v_pk_fma_f32 v[218:219], v[72:73], v[12:13], v[218:219] op_sel_hi:[1,0,1]
	v_pk_fma_f32 v[220:221], v[74:75], v[12:13], v[220:221] op_sel:[0,1,0] op_sel_hi:[1,1,1]
	v_pk_fma_f32 v[222:223], v[76:77], v[14:15], v[222:223] op_sel_hi:[1,0,1]
	v_pk_fma_f32 v[224:225], v[78:79], v[14:15], v[224:225] op_sel:[0,1,0] op_sel_hi:[1,1,1]
	v_add_f32_dpp v164, v164, v164 quad_perm:[1,0,3,2] row_mask:0xf bank_mask:0xf bound_ctrl:1
	v_add_f32_dpp v165, v165, v165 quad_perm:[1,0,3,2] row_mask:0xf bank_mask:0xf bound_ctrl:1
	v_add_f32_dpp v160, v160, v160 quad_perm:[1,0,3,2] row_mask:0xf bank_mask:0xf bound_ctrl:1
	v_add_f32_dpp v161, v161, v161 quad_perm:[1,0,3,2] row_mask:0xf bank_mask:0xf bound_ctrl:1
	v_pk_fma_f32 v[226:227], v[80:81], v[28:29], v[226:227] op_sel_hi:[1,0,1]
	v_pk_fma_f32 v[228:229], v[82:83], v[28:29], v[228:229] op_sel:[0,1,0] op_sel_hi:[1,1,1]
	v_pk_fma_f32 v[230:231], v[84:85], v[30:31], v[230:231] op_sel_hi:[1,0,1]
	v_pk_fma_f32 v[234:235], v[86:87], v[30:31], v[234:235] op_sel:[0,1,0] op_sel_hi:[1,1,1]
	v_add_f32_dpp v164, v164, v164 quad_perm:[2,3,0,1] row_mask:0xf bank_mask:0xf bound_ctrl:1
	v_add_f32_dpp v165, v165, v165 quad_perm:[2,3,0,1] row_mask:0xf bank_mask:0xf bound_ctrl:1
	v_add_f32_dpp v160, v160, v160 quad_perm:[2,3,0,1] row_mask:0xf bank_mask:0xf bound_ctrl:1
	v_add_f32_dpp v161, v161, v161 quad_perm:[2,3,0,1] row_mask:0xf bank_mask:0xf bound_ctrl:1
	v_add_f32_dpp v164, v164, v164 row_half_mirror row_mask:0xf bank_mask:0xf bound_ctrl:1
	v_add_f32_dpp v165, v165, v165 row_half_mirror row_mask:0xf bank_mask:0xf bound_ctrl:1
	v_add_f32_dpp v160, v160, v160 row_half_mirror row_mask:0xf bank_mask:0xf bound_ctrl:1
	v_add_f32_dpp v161, v161, v161 row_half_mirror row_mask:0xf bank_mask:0xf bound_ctrl:1
	v_pk_fma_f32 v[72:73], v[32:33], v[164:165], v[218:219] op_sel_hi:[0,1,1]
	v_pk_fma_f32 v[74:75], v[32:33], v[164:165], v[220:221] op_sel:[1,0,0] op_sel_hi:[1,1,1]
	v_pk_fma_f32 v[76:77], v[34:35], v[164:165], v[222:223] op_sel_hi:[0,1,1]
	v_pk_fma_f32 v[78:79], v[34:35], v[164:165], v[224:225] op_sel:[1,0,0] op_sel_hi:[1,1,1]
	v_pk_fma_f32 v[80:81], v[36:37], v[164:165], v[226:227] op_sel_hi:[0,1,1]
	v_pk_fma_f32 v[82:83], v[36:37], v[164:165], v[228:229] op_sel:[1,0,0] op_sel_hi:[1,1,1]
	v_pk_fma_f32 v[84:85], v[38:39], v[164:165], v[230:231] op_sel_hi:[0,1,1]
	v_pk_fma_f32 v[86:87], v[38:39], v[164:165], v[234:235] op_sel:[1,0,0] op_sel_hi:[1,1,1]
	ds_write_b64 v1, v[160:161] offset:57088
	s_waitcnt lgkmcnt(1)
	v_pk_mul_f32 v[164:165], v[72:73], v[176:177] op_sel_hi:[1,0]
	v_pk_mul_f32 v[160:161], v[72:73], v[48:49] op_sel_hi:[1,0]
	ds_read_b128 v[208:211], v2 offset:19968
	v_pk_fma_f32 v[164:165], v[74:75], v[176:177], v[164:165] op_sel:[0,1,0] op_sel_hi:[1,1,1]
	v_pk_fma_f32 v[160:161], v[74:75], v[48:49], v[160:161] op_sel:[0,1,0] op_sel_hi:[1,1,1]
	ds_read_b128 v[212:215], v2 offset:19984
	v_pk_fma_f32 v[164:165], v[76:77], v[178:179], v[164:165] op_sel_hi:[1,0,1]
	v_pk_fma_f32 v[160:161], v[76:77], v[50:51], v[160:161] op_sel_hi:[1,0,1]
	ds_read_b128 v[4:7], v2 offset:7936
	v_pk_fma_f32 v[164:165], v[78:79], v[178:179], v[164:165] op_sel:[0,1,0] op_sel_hi:[1,1,1]
	v_pk_fma_f32 v[160:161], v[78:79], v[50:51], v[160:161] op_sel:[0,1,0] op_sel_hi:[1,1,1]
	ds_read_b128 v[8:11], v2 offset:7952
	v_pk_fma_f32 v[164:165], v[80:81], v[180:181], v[164:165] op_sel_hi:[1,0,1]
	v_pk_fma_f32 v[160:161], v[80:81], v[52:53], v[160:161] op_sel_hi:[1,0,1]
	ds_read_b128 v[40:43], v2 offset:16128
	v_pk_fma_f32 v[164:165], v[82:83], v[180:181], v[164:165] op_sel:[0,1,0] op_sel_hi:[1,1,1]
	v_pk_fma_f32 v[160:161], v[82:83], v[52:53], v[160:161] op_sel:[0,1,0] op_sel_hi:[1,1,1]
	ds_read_b128 v[44:47], v2 offset:16144
	v_pk_fma_f32 v[164:165], v[84:85], v[182:183], v[164:165] op_sel_hi:[1,0,1]
	v_pk_fma_f32 v[160:161], v[84:85], v[54:55], v[160:161] op_sel_hi:[1,0,1]
	ds_read_b64 v[26:27], v3 offset:44800
	v_pk_fma_f32 v[164:165], v[86:87], v[182:183], v[164:165] op_sel:[0,1,0] op_sel_hi:[1,1,1]
	v_pk_fma_f32 v[160:161], v[86:87], v[54:55], v[160:161] op_sel:[0,1,0] op_sel_hi:[1,1,1]
	ds_read_b128 v[12:15], v2 offset:3840
	v_pk_mul_f32 v[218:219], v[216:217], v[200:201] op_sel_hi:[1,0]
	v_pk_mul_f32 v[220:221], v[216:217], v[200:201] op_sel:[0,1] op_sel_hi:[1,1]
	ds_read_b128 v[28:31], v2 offset:3856
	v_pk_mul_f32 v[222:223], v[216:217], v[202:203] op_sel_hi:[1,0]
	v_pk_mul_f32 v[224:225], v[216:217], v[202:203] op_sel:[0,1] op_sel_hi:[1,1]
	ds_read_b128 v[32:35], v2 offset:12032
	v_pk_mul_f32 v[226:227], v[216:217], v[204:205] op_sel_hi:[1,0]
	v_pk_mul_f32 v[228:229], v[216:217], v[204:205] op_sel:[0,1] op_sel_hi:[1,1]
	ds_read_b128 v[36:39], v2 offset:12048
	v_pk_mul_f32 v[230:231], v[216:217], v[206:207] op_sel_hi:[1,0]
	v_pk_mul_f32 v[234:235], v[216:217], v[206:207] op_sel:[0,1] op_sel_hi:[1,1]
	v_pk_fma_f32 v[218:219], v[72:73], v[184:185], v[218:219] op_sel_hi:[1,0,1]
	v_pk_fma_f32 v[220:221], v[74:75], v[184:185], v[220:221] op_sel:[0,1,0] op_sel_hi:[1,1,1]
	v_pk_fma_f32 v[222:223], v[76:77], v[186:187], v[222:223] op_sel_hi:[1,0,1]
	v_pk_fma_f32 v[224:225], v[78:79], v[186:187], v[224:225] op_sel:[0,1,0] op_sel_hi:[1,1,1]
	v_add_f32_dpp v164, v164, v164 quad_perm:[1,0,3,2] row_mask:0xf bank_mask:0xf bound_ctrl:1
	v_add_f32_dpp v165, v165, v165 quad_perm:[1,0,3,2] row_mask:0xf bank_mask:0xf bound_ctrl:1
	v_add_f32_dpp v160, v160, v160 quad_perm:[1,0,3,2] row_mask:0xf bank_mask:0xf bound_ctrl:1
	v_add_f32_dpp v161, v161, v161 quad_perm:[1,0,3,2] row_mask:0xf bank_mask:0xf bound_ctrl:1
	v_pk_fma_f32 v[226:227], v[80:81], v[188:189], v[226:227] op_sel_hi:[1,0,1]
	v_pk_fma_f32 v[228:229], v[82:83], v[188:189], v[228:229] op_sel:[0,1,0] op_sel_hi:[1,1,1]
	v_pk_fma_f32 v[230:231], v[84:85], v[190:191], v[230:231] op_sel_hi:[1,0,1]
	v_pk_fma_f32 v[234:235], v[86:87], v[190:191], v[234:235] op_sel:[0,1,0] op_sel_hi:[1,1,1]
	v_add_f32_dpp v164, v164, v164 quad_perm:[2,3,0,1] row_mask:0xf bank_mask:0xf bound_ctrl:1
	v_add_f32_dpp v165, v165, v165 quad_perm:[2,3,0,1] row_mask:0xf bank_mask:0xf bound_ctrl:1
	v_add_f32_dpp v160, v160, v160 quad_perm:[2,3,0,1] row_mask:0xf bank_mask:0xf bound_ctrl:1
	v_add_f32_dpp v161, v161, v161 quad_perm:[2,3,0,1] row_mask:0xf bank_mask:0xf bound_ctrl:1
	v_add_f32_dpp v164, v164, v164 row_half_mirror row_mask:0xf bank_mask:0xf bound_ctrl:1
	v_add_f32_dpp v165, v165, v165 row_half_mirror row_mask:0xf bank_mask:0xf bound_ctrl:1
	v_add_f32_dpp v160, v160, v160 row_half_mirror row_mask:0xf bank_mask:0xf bound_ctrl:1
	v_add_f32_dpp v161, v161, v161 row_half_mirror row_mask:0xf bank_mask:0xf bound_ctrl:1
	v_pk_fma_f32 v[72:73], v[192:193], v[164:165], v[218:219] op_sel_hi:[0,1,1]
	v_pk_fma_f32 v[74:75], v[192:193], v[164:165], v[220:221] op_sel:[1,0,0] op_sel_hi:[1,1,1]
	v_pk_fma_f32 v[76:77], v[194:195], v[164:165], v[222:223] op_sel_hi:[0,1,1]
	v_pk_fma_f32 v[78:79], v[194:195], v[164:165], v[224:225] op_sel:[1,0,0] op_sel_hi:[1,1,1]
	v_pk_fma_f32 v[80:81], v[196:197], v[164:165], v[226:227] op_sel_hi:[0,1,1]
	v_pk_fma_f32 v[82:83], v[196:197], v[164:165], v[228:229] op_sel:[1,0,0] op_sel_hi:[1,1,1]
	v_pk_fma_f32 v[84:85], v[198:199], v[164:165], v[230:231] op_sel_hi:[0,1,1]
	v_pk_fma_f32 v[86:87], v[198:199], v[164:165], v[234:235] op_sel:[1,0,0] op_sel_hi:[1,1,1]
	ds_write_b64 v1, v[160:161] offset:57344
	s_waitcnt lgkmcnt(1)
	v_pk_mul_f32 v[164:165], v[72:73], v[4:5] op_sel_hi:[1,0]
	v_pk_mul_f32 v[160:161], v[72:73], v[208:209] op_sel_hi:[1,0]
	ds_read_b128 v[48:51], v2 offset:20224
	v_pk_fma_f32 v[164:165], v[74:75], v[4:5], v[164:165] op_sel:[0,1,0] op_sel_hi:[1,1,1]
	v_pk_fma_f32 v[160:161], v[74:75], v[208:209], v[160:161] op_sel:[0,1,0] op_sel_hi:[1,1,1]
	ds_read_b128 v[52:55], v2 offset:20240
	v_pk_fma_f32 v[164:165], v[76:77], v[6:7], v[164:165] op_sel_hi:[1,0,1]
	v_pk_fma_f32 v[160:161], v[76:77], v[210:211], v[160:161] op_sel_hi:[1,0,1]
	v_pk_fma_f32 v[164:165], v[78:79], v[6:7], v[164:165] op_sel:[0,1,0] op_sel_hi:[1,1,1]
	v_pk_fma_f32 v[160:161], v[78:79], v[210:211], v[160:161] op_sel:[0,1,0] op_sel_hi:[1,1,1]
	v_pk_fma_f32 v[164:165], v[80:81], v[8:9], v[164:165] op_sel_hi:[1,0,1]
	v_pk_fma_f32 v[160:161], v[80:81], v[212:213], v[160:161] op_sel_hi:[1,0,1]
	v_pk_fma_f32 v[164:165], v[82:83], v[8:9], v[164:165] op_sel:[0,1,0] op_sel_hi:[1,1,1]
	v_pk_fma_f32 v[160:161], v[82:83], v[212:213], v[160:161] op_sel:[0,1,0] op_sel_hi:[1,1,1]
	v_pk_fma_f32 v[164:165], v[84:85], v[10:11], v[164:165] op_sel_hi:[1,0,1]
	v_pk_fma_f32 v[160:161], v[84:85], v[214:215], v[160:161] op_sel_hi:[1,0,1]
	v_pk_fma_f32 v[164:165], v[86:87], v[10:11], v[164:165] op_sel:[0,1,0] op_sel_hi:[1,1,1]
	v_pk_fma_f32 v[160:161], v[86:87], v[214:215], v[160:161] op_sel:[0,1,0] op_sel_hi:[1,1,1]
	v_pk_mul_f32 v[218:219], v[26:27], v[40:41] op_sel_hi:[1,0]
	v_pk_mul_f32 v[220:221], v[26:27], v[40:41] op_sel:[0,1] op_sel_hi:[1,1]
	v_pk_mul_f32 v[222:223], v[26:27], v[42:43] op_sel_hi:[1,0]
	v_pk_mul_f32 v[224:225], v[26:27], v[42:43] op_sel:[0,1] op_sel_hi:[1,1]
	v_pk_mul_f32 v[226:227], v[26:27], v[44:45] op_sel_hi:[1,0]
	v_pk_mul_f32 v[228:229], v[26:27], v[44:45] op_sel:[0,1] op_sel_hi:[1,1]
	v_pk_mul_f32 v[230:231], v[26:27], v[46:47] op_sel_hi:[1,0]
	v_pk_mul_f32 v[234:235], v[26:27], v[46:47] op_sel:[0,1] op_sel_hi:[1,1]
	v_pk_fma_f32 v[218:219], v[72:73], v[12:13], v[218:219] op_sel_hi:[1,0,1]
	v_pk_fma_f32 v[220:221], v[74:75], v[12:13], v[220:221] op_sel:[0,1,0] op_sel_hi:[1,1,1]
	v_pk_fma_f32 v[222:223], v[76:77], v[14:15], v[222:223] op_sel_hi:[1,0,1]
	v_pk_fma_f32 v[224:225], v[78:79], v[14:15], v[224:225] op_sel:[0,1,0] op_sel_hi:[1,1,1]
	v_add_f32_dpp v164, v164, v164 quad_perm:[1,0,3,2] row_mask:0xf bank_mask:0xf bound_ctrl:1
	v_add_f32_dpp v165, v165, v165 quad_perm:[1,0,3,2] row_mask:0xf bank_mask:0xf bound_ctrl:1
	v_add_f32_dpp v160, v160, v160 quad_perm:[1,0,3,2] row_mask:0xf bank_mask:0xf bound_ctrl:1
	v_add_f32_dpp v161, v161, v161 quad_perm:[1,0,3,2] row_mask:0xf bank_mask:0xf bound_ctrl:1
	v_pk_fma_f32 v[226:227], v[80:81], v[28:29], v[226:227] op_sel_hi:[1,0,1]
	v_pk_fma_f32 v[228:229], v[82:83], v[28:29], v[228:229] op_sel:[0,1,0] op_sel_hi:[1,1,1]
	v_pk_fma_f32 v[230:231], v[84:85], v[30:31], v[230:231] op_sel_hi:[1,0,1]
	v_pk_fma_f32 v[234:235], v[86:87], v[30:31], v[234:235] op_sel:[0,1,0] op_sel_hi:[1,1,1]
	v_add_f32_dpp v164, v164, v164 quad_perm:[2,3,0,1] row_mask:0xf bank_mask:0xf bound_ctrl:1
	v_add_f32_dpp v165, v165, v165 quad_perm:[2,3,0,1] row_mask:0xf bank_mask:0xf bound_ctrl:1
	v_add_f32_dpp v160, v160, v160 quad_perm:[2,3,0,1] row_mask:0xf bank_mask:0xf bound_ctrl:1
	v_add_f32_dpp v161, v161, v161 quad_perm:[2,3,0,1] row_mask:0xf bank_mask:0xf bound_ctrl:1
	v_add_f32_dpp v164, v164, v164 row_half_mirror row_mask:0xf bank_mask:0xf bound_ctrl:1
	v_add_f32_dpp v165, v165, v165 row_half_mirror row_mask:0xf bank_mask:0xf bound_ctrl:1
	v_add_f32_dpp v160, v160, v160 row_half_mirror row_mask:0xf bank_mask:0xf bound_ctrl:1
	v_add_f32_dpp v161, v161, v161 row_half_mirror row_mask:0xf bank_mask:0xf bound_ctrl:1
	v_pk_fma_f32 v[72:73], v[32:33], v[164:165], v[218:219] op_sel_hi:[0,1,1]
	v_pk_fma_f32 v[74:75], v[32:33], v[164:165], v[220:221] op_sel:[1,0,0] op_sel_hi:[1,1,1]
	v_pk_fma_f32 v[76:77], v[34:35], v[164:165], v[222:223] op_sel_hi:[0,1,1]
	v_pk_fma_f32 v[78:79], v[34:35], v[164:165], v[224:225] op_sel:[1,0,0] op_sel_hi:[1,1,1]
	v_pk_fma_f32 v[80:81], v[36:37], v[164:165], v[226:227] op_sel_hi:[0,1,1]
	v_pk_fma_f32 v[82:83], v[36:37], v[164:165], v[228:229] op_sel:[1,0,0] op_sel_hi:[1,1,1]
	v_pk_fma_f32 v[84:85], v[38:39], v[164:165], v[230:231] op_sel_hi:[0,1,1]
	v_pk_fma_f32 v[86:87], v[38:39], v[164:165], v[234:235] op_sel:[1,0,0] op_sel_hi:[1,1,1]
	ds_write_b64 v1, v[160:161] offset:57600
	s_waitcnt lgkmcnt(2)
	v_pk_mul_f32 v[160:161], v[72:73], v[48:49] op_sel_hi:[1,0]
	v_pk_fma_f32 v[160:161], v[74:75], v[48:49], v[160:161] op_sel:[0,1,0] op_sel_hi:[1,1,1]
	v_pk_fma_f32 v[160:161], v[76:77], v[50:51], v[160:161] op_sel_hi:[1,0,1]
	v_pk_fma_f32 v[160:161], v[78:79], v[50:51], v[160:161] op_sel:[0,1,0] op_sel_hi:[1,1,1]
	s_waitcnt lgkmcnt(1)
	v_pk_fma_f32 v[160:161], v[80:81], v[52:53], v[160:161] op_sel_hi:[1,0,1]
	v_pk_fma_f32 v[160:161], v[82:83], v[52:53], v[160:161] op_sel:[0,1,0] op_sel_hi:[1,1,1]
	v_pk_fma_f32 v[160:161], v[84:85], v[54:55], v[160:161] op_sel_hi:[1,0,1]
	v_pk_fma_f32 v[160:161], v[86:87], v[54:55], v[160:161] op_sel:[0,1,0] op_sel_hi:[1,1,1]
	s_nop 1
	v_add_f32_dpp v160, v160, v160 quad_perm:[1,0,3,2] row_mask:0xf bank_mask:0xf bound_ctrl:1
	v_add_f32_dpp v161, v161, v161 quad_perm:[1,0,3,2] row_mask:0xf bank_mask:0xf bound_ctrl:1
	s_nop 0
	v_add_f32_dpp v160, v160, v160 quad_perm:[2,3,0,1] row_mask:0xf bank_mask:0xf bound_ctrl:1
	v_add_f32_dpp v161, v161, v161 quad_perm:[2,3,0,1] row_mask:0xf bank_mask:0xf bound_ctrl:1
	s_nop 0
	v_add_f32_dpp v160, v160, v160 row_half_mirror row_mask:0xf bank_mask:0xf bound_ctrl:1
	v_add_f32_dpp v161, v161, v161 row_half_mirror row_mask:0xf bank_mask:0xf bound_ctrl:1
	ds_write_b64 v1, v[160:161] offset:57856
	s_add_i32 s3, s2, 1
	s_mov_b64 s[36:37], 0
